# accumulator zeroing removed: first four phases of each tile peeled with SrcC=0 MFMAs, K-loop entered at phase 5 (all 6 GEMM phases)
# speedup vs baseline: 1.0513x; 1.0029x over previous
.LBB0_130:
	s_ashr_i32 s13, s12, 31
	v_cmp_lt_i64_e32 vcc, s[14:15], v[140:141]
	s_lshl_b64 s[14:15], s[12:13], 19
	s_add_u32 s14, s39, s14
	s_addc_u32 s15, s40, s15
	s_and_b64 s[16:17], vcc, exec
	s_cselect_b32 s13, s15, s21
	s_cselect_b32 s53, s14, s20
	s_ashr_i32 s11, s10, 31
	s_lshl_b64 s[16:17], s[10:11], 19
	s_add_u32 s16, s33, s16
	s_addc_u32 s17, s34, s17
	s_and_b64 s[28:29], vcc, exec
	s_cselect_b32 s11, s17, s27
	s_cselect_b32 s54, s16, s26
	s_add_u32 s20, s20, 0x40080
	s_addc_u32 s21, s21, 0
	s_add_u32 s55, s26, 0x100
	s_addc_u32 s56, s27, 0
	s_mov_b32 s57, -2
	s_cmpk_lt_u32 s37, 0x100
	s_cbranch_scc1 .Lg131_noy
	s_barrier
.Lg131_noy:
	ds_read_b128 v[152:155], v149
	ds_read_b128 v[156:159], v149 offset:1024
	ds_read_b128 v[160:163], v149 offset:2048
	ds_read_b128 v[164:167], v149 offset:3072
	s_add_u32 s26, s20, 0xfffc0080
	s_addc_u32 s27, s21, -1
	s_cmp_eq_u32 s57, 12
	s_cselect_b32 s29, s13, s27
	s_cselect_b32 s28, s53, s26
	s_cselect_b32 s27, s11, s56
	s_cselect_b32 s26, s54, s55
	s_add_i32 m0, s19, 0xc000
	ds_read_b128 v[168:171], v150
	ds_read_b128 v[172:175], v150 offset:1024
	ds_read_b128 v[176:179], v150 offset:2048
	ds_read_b128 v[180:183], v150 offset:3072
	ds_read_b128 v[184:187], v150 offset:4096
	ds_read_b128 v[188:191], v150 offset:5120
	ds_read_b128 v[192:195], v150 offset:6144
	ds_read_b128 v[196:199], v150 offset:7168
	global_load_lds_dwordx4 v136, s[20:21]
	s_add_i32 m0, s19, 0xe000
	s_nop 0
	global_load_lds_dwordx4 v138, s[20:21]
	s_waitcnt lgkmcnt(8)
	s_barrier
	s_waitcnt lgkmcnt(0)
	s_setprio 1
	s_waitcnt lgkmcnt(0)
	v_mfma_f32_16x16x32_bf16 v[124:127], v[152:155], v[168:171], 0
	v_mfma_f32_16x16x32_bf16 v[120:123], v[160:163], v[168:171], 0
	v_mfma_f32_16x16x32_bf16 v[108:111], v[152:155], v[176:179], 0
	v_mfma_f32_16x16x32_bf16 v[104:107], v[160:163], v[176:179], 0
	v_mfma_f32_16x16x32_bf16 v[92:95], v[152:155], v[184:187], 0
	v_mfma_f32_16x16x32_bf16 v[88:91], v[160:163], v[184:187], 0
	v_mfma_f32_16x16x32_bf16 v[76:79], v[152:155], v[192:195], 0
	v_mfma_f32_16x16x32_bf16 v[72:75], v[160:163], v[192:195], 0
	v_mfma_f32_16x16x32_bf16 v[124:127], v[156:159], v[172:175], v[124:127]
	v_mfma_f32_16x16x32_bf16 v[120:123], v[164:167], v[172:175], v[120:123]
	v_mfma_f32_16x16x32_bf16 v[108:111], v[156:159], v[180:183], v[108:111]
	v_mfma_f32_16x16x32_bf16 v[104:107], v[164:167], v[180:183], v[104:107]
	v_mfma_f32_16x16x32_bf16 v[92:95], v[156:159], v[188:191], v[92:95]
	v_mfma_f32_16x16x32_bf16 v[88:91], v[164:167], v[188:191], v[88:91]
	v_mfma_f32_16x16x32_bf16 v[76:79], v[156:159], v[196:199], v[76:79]
	v_mfma_f32_16x16x32_bf16 v[72:75], v[164:167], v[196:199], v[72:75]
	s_setprio 0
	s_barrier
	s_add_i32 s58, s47, s38
	s_add_u32 s80, s26, 0x80
	s_addc_u32 s81, s27, 0
	s_mov_b32 m0, s58
	ds_read_b128 v[200:203], v151
	ds_read_b128 v[204:207], v151 offset:1024
	ds_read_b128 v[208:211], v151 offset:2048
	ds_read_b128 v[212:215], v151 offset:3072
	global_load_lds_dwordx4 v132, s[26:27]
	s_add_i32 m0, s58, 0x2000
	s_nop 0
	global_load_lds_dwordx4 v128, s[26:27]
	s_barrier
	s_waitcnt lgkmcnt(0)
	s_setprio 1
	s_waitcnt lgkmcnt(0)
	v_mfma_f32_16x16x32_bf16 v[116:119], v[200:203], v[168:171], 0
	v_mfma_f32_16x16x32_bf16 v[112:115], v[208:211], v[168:171], 0
	v_mfma_f32_16x16x32_bf16 v[100:103], v[200:203], v[176:179], 0
	v_mfma_f32_16x16x32_bf16 v[96:99], v[208:211], v[176:179], 0
	v_mfma_f32_16x16x32_bf16 v[84:87], v[200:203], v[184:187], 0
	v_mfma_f32_16x16x32_bf16 v[80:83], v[208:211], v[184:187], 0
	v_mfma_f32_16x16x32_bf16 v[68:71], v[200:203], v[192:195], 0
	v_mfma_f32_16x16x32_bf16 v[64:67], v[208:211], v[192:195], 0
	v_mfma_f32_16x16x32_bf16 v[116:119], v[204:207], v[172:175], v[116:119]
	v_mfma_f32_16x16x32_bf16 v[112:115], v[212:215], v[172:175], v[112:115]
	v_mfma_f32_16x16x32_bf16 v[100:103], v[204:207], v[180:183], v[100:103]
	v_mfma_f32_16x16x32_bf16 v[96:99], v[212:215], v[180:183], v[96:99]
	v_mfma_f32_16x16x32_bf16 v[84:87], v[204:207], v[188:191], v[84:87]
	v_mfma_f32_16x16x32_bf16 v[80:83], v[212:215], v[188:191], v[80:83]
	v_mfma_f32_16x16x32_bf16 v[68:71], v[204:207], v[196:199], v[68:71]
	v_mfma_f32_16x16x32_bf16 v[64:67], v[212:215], v[196:199], v[64:67]
	s_setprio 0
	s_mov_b32 m0, s19
	s_add_u32 s82, s28, 0x80
	s_addc_u32 s83, s29, 0
	s_barrier
	ds_read_b128 v[168:171], v150 offset:16384
	ds_read_b128 v[172:175], v150 offset:17408
	ds_read_b128 v[176:179], v150 offset:18432
	ds_read_b128 v[180:183], v150 offset:19456
	ds_read_b128 v[184:187], v150 offset:20480
	ds_read_b128 v[188:191], v150 offset:21504
	ds_read_b128 v[192:195], v150 offset:22528
	ds_read_b128 v[196:199], v150 offset:23552
	global_load_lds_dwordx4 v134, s[28:29]
	s_mov_b32 m0, s42
	s_nop 0
	global_load_lds_dwordx4 v130, s[28:29]
	s_barrier
	s_waitcnt lgkmcnt(0)
	s_setprio 1
	s_waitcnt lgkmcnt(0)
	v_mfma_f32_16x16x32_bf16 v[60:63], v[152:155], v[168:171], 0
	v_mfma_f32_16x16x32_bf16 v[56:59], v[160:163], v[168:171], 0
	v_mfma_f32_16x16x32_bf16 v[44:47], v[152:155], v[176:179], 0
	v_mfma_f32_16x16x32_bf16 v[40:43], v[160:163], v[176:179], 0
	v_mfma_f32_16x16x32_bf16 v[28:31], v[152:155], v[184:187], 0
	v_mfma_f32_16x16x32_bf16 v[24:27], v[160:163], v[184:187], 0
	v_mfma_f32_16x16x32_bf16 v[12:15], v[152:155], v[192:195], 0
	v_mfma_f32_16x16x32_bf16 v[8:11], v[160:163], v[192:195], 0
	v_mfma_f32_16x16x32_bf16 v[60:63], v[156:159], v[172:175], v[60:63]
	v_mfma_f32_16x16x32_bf16 v[56:59], v[164:167], v[172:175], v[56:59]
	v_mfma_f32_16x16x32_bf16 v[44:47], v[156:159], v[180:183], v[44:47]
	v_mfma_f32_16x16x32_bf16 v[40:43], v[164:167], v[180:183], v[40:43]
	v_mfma_f32_16x16x32_bf16 v[28:31], v[156:159], v[188:191], v[28:31]
	v_mfma_f32_16x16x32_bf16 v[24:27], v[164:167], v[188:191], v[24:27]
	v_mfma_f32_16x16x32_bf16 v[12:15], v[156:159], v[196:199], v[12:15]
	v_mfma_f32_16x16x32_bf16 v[8:11], v[164:167], v[196:199], v[8:11]
	s_setprio 0
	s_barrier
	s_add_u32 s58, s26, 0x40000
	s_addc_u32 s59, s27, 0
	s_add_i32 s60, s48, s38
	s_mov_b32 m0, s60
	s_nop 0
	global_load_lds_dwordx4 v132, s[58:59]
	s_add_i32 m0, s60, 0x2000
	s_nop 0
	global_load_lds_dwordx4 v128, s[58:59]
	s_waitcnt vmcnt(6)
	s_barrier
	s_setprio 1
	v_mfma_f32_16x16x32_bf16 v[52:55], v[200:203], v[168:171], 0
	v_mfma_f32_16x16x32_bf16 v[48:51], v[208:211], v[168:171], 0
	v_mfma_f32_16x16x32_bf16 v[36:39], v[200:203], v[176:179], 0
	v_mfma_f32_16x16x32_bf16 v[32:35], v[208:211], v[176:179], 0
	v_mfma_f32_16x16x32_bf16 v[20:23], v[200:203], v[184:187], 0
	v_mfma_f32_16x16x32_bf16 v[16:19], v[208:211], v[184:187], 0
	v_mfma_f32_16x16x32_bf16 v[4:7], v[200:203], v[192:195], 0
	v_mfma_f32_16x16x32_bf16 v[0:3], v[208:211], v[192:195], 0
	v_mfma_f32_16x16x32_bf16 v[52:55], v[204:207], v[172:175], v[52:55]
	v_mfma_f32_16x16x32_bf16 v[48:51], v[212:215], v[172:175], v[48:51]
	v_mfma_f32_16x16x32_bf16 v[36:39], v[204:207], v[180:183], v[36:39]
	v_mfma_f32_16x16x32_bf16 v[32:35], v[212:215], v[180:183], v[32:35]
	v_mfma_f32_16x16x32_bf16 v[20:23], v[204:207], v[188:191], v[20:23]
	v_mfma_f32_16x16x32_bf16 v[16:19], v[212:215], v[188:191], v[16:19]
	v_mfma_f32_16x16x32_bf16 v[4:7], v[204:207], v[196:199], v[4:7]
	v_mfma_f32_16x16x32_bf16 v[0:3], v[212:215], v[196:199], v[0:3]
	s_setprio 0
	s_add_i32 s58, 0, 0x18000
	v_add_u32_e32 v164, s58, v145
	s_barrier
	s_branch .Lg131_mid

.Lg131_mid:
	ds_read_b128 v[152:155], v164
	ds_read_b128 v[156:159], v164 offset:1024
	ds_read_b128 v[160:163], v164 offset:2048
	ds_read_b128 v[164:167], v164 offset:3072
	s_add_u32 s28, s28, 0x40000
	s_addc_u32 s29, s29, 0
	s_mov_b32 m0, s43
	ds_read_b128 v[168:171], v150 offset:32768
	ds_read_b128 v[172:175], v150 offset:33792
	ds_read_b128 v[176:179], v150 offset:34816
	ds_read_b128 v[180:183], v150 offset:35840
	ds_read_b128 v[184:187], v150 offset:36864
	ds_read_b128 v[188:191], v150 offset:37888
	ds_read_b128 v[192:195], v150 offset:38912
	ds_read_b128 v[196:199], v150 offset:39936
	global_load_lds_dwordx4 v134, s[28:29]
	s_mov_b32 m0, s44
	s_nop 0
	global_load_lds_dwordx4 v130, s[28:29]
	s_waitcnt lgkmcnt(8)
	s_barrier
	s_waitcnt lgkmcnt(0)
	s_setprio 1
	s_waitcnt lgkmcnt(0)
	v_mfma_f32_16x16x32_bf16 v[124:127], v[152:155], v[168:171], v[124:127]
	v_mfma_f32_16x16x32_bf16 v[120:123], v[160:163], v[168:171], v[120:123]
	v_mfma_f32_16x16x32_bf16 v[108:111], v[152:155], v[176:179], v[108:111]
	v_mfma_f32_16x16x32_bf16 v[104:107], v[160:163], v[176:179], v[104:107]
	v_mfma_f32_16x16x32_bf16 v[92:95], v[152:155], v[184:187], v[92:95]
	v_mfma_f32_16x16x32_bf16 v[88:91], v[160:163], v[184:187], v[88:91]
	v_mfma_f32_16x16x32_bf16 v[76:79], v[152:155], v[192:195], v[76:79]
	v_mfma_f32_16x16x32_bf16 v[72:75], v[160:163], v[192:195], v[72:75]
	v_mfma_f32_16x16x32_bf16 v[124:127], v[156:159], v[172:175], v[124:127]
	v_mfma_f32_16x16x32_bf16 v[120:123], v[164:167], v[172:175], v[120:123]
	v_mfma_f32_16x16x32_bf16 v[108:111], v[156:159], v[180:183], v[108:111]
	v_mfma_f32_16x16x32_bf16 v[104:107], v[164:167], v[180:183], v[104:107]
	v_mfma_f32_16x16x32_bf16 v[92:95], v[156:159], v[188:191], v[92:95]
	v_mfma_f32_16x16x32_bf16 v[88:91], v[164:167], v[188:191], v[88:91]
	v_mfma_f32_16x16x32_bf16 v[76:79], v[156:159], v[196:199], v[76:79]
	v_mfma_f32_16x16x32_bf16 v[72:75], v[164:167], v[196:199], v[72:75]
	s_setprio 0
	s_barrier
	s_add_i32 s28, 0, 0x1c000
	s_add_i32 s29, s58, s38
	v_add_u32_e32 v212, s28, v145
	s_mov_b32 m0, s29
	ds_read_b128 v[200:203], v212
	ds_read_b128 v[204:207], v212 offset:1024
	ds_read_b128 v[208:211], v212 offset:2048
	ds_read_b128 v[212:215], v212 offset:3072
	global_load_lds_dwordx4 v132, s[80:81]
	s_add_i32 m0, s29, 0x2000
	s_nop 0
	global_load_lds_dwordx4 v128, s[80:81]
	s_barrier
	s_waitcnt lgkmcnt(0)
	s_setprio 1
	s_waitcnt lgkmcnt(0)
	v_mfma_f32_16x16x32_bf16 v[116:119], v[200:203], v[168:171], v[116:119]
	v_mfma_f32_16x16x32_bf16 v[112:115], v[208:211], v[168:171], v[112:115]
	v_mfma_f32_16x16x32_bf16 v[100:103], v[200:203], v[176:179], v[100:103]
	v_mfma_f32_16x16x32_bf16 v[96:99], v[208:211], v[176:179], v[96:99]
	v_mfma_f32_16x16x32_bf16 v[84:87], v[200:203], v[184:187], v[84:87]
	v_mfma_f32_16x16x32_bf16 v[80:83], v[208:211], v[184:187], v[80:83]
	v_mfma_f32_16x16x32_bf16 v[68:71], v[200:203], v[192:195], v[68:71]
	v_mfma_f32_16x16x32_bf16 v[64:67], v[208:211], v[192:195], v[64:67]
	v_mfma_f32_16x16x32_bf16 v[116:119], v[204:207], v[172:175], v[116:119]
	v_mfma_f32_16x16x32_bf16 v[112:115], v[212:215], v[172:175], v[112:115]
	v_mfma_f32_16x16x32_bf16 v[100:103], v[204:207], v[180:183], v[100:103]
	v_mfma_f32_16x16x32_bf16 v[96:99], v[212:215], v[180:183], v[96:99]
	v_mfma_f32_16x16x32_bf16 v[84:87], v[204:207], v[188:191], v[84:87]
	v_mfma_f32_16x16x32_bf16 v[80:83], v[212:215], v[188:191], v[80:83]
	v_mfma_f32_16x16x32_bf16 v[68:71], v[204:207], v[196:199], v[68:71]
	v_mfma_f32_16x16x32_bf16 v[64:67], v[212:215], v[196:199], v[64:67]
	s_setprio 0
	s_mov_b32 m0, s45
	s_barrier
	ds_read_b128 v[168:171], v150 offset:49152
	ds_read_b128 v[172:175], v150 offset:50176
	ds_read_b128 v[176:179], v150 offset:51200
	ds_read_b128 v[180:183], v150 offset:52224
	ds_read_b128 v[184:187], v150 offset:53248
	ds_read_b128 v[188:191], v150 offset:54272
	ds_read_b128 v[192:195], v150 offset:55296
	ds_read_b128 v[196:199], v150 offset:56320
	global_load_lds_dwordx4 v134, s[82:83]
	s_mov_b32 m0, s46
	s_nop 0
	global_load_lds_dwordx4 v130, s[82:83]
	s_barrier
	s_waitcnt lgkmcnt(0)
	s_setprio 1
	s_waitcnt lgkmcnt(0)
	v_mfma_f32_16x16x32_bf16 v[60:63], v[152:155], v[168:171], v[60:63]
	v_mfma_f32_16x16x32_bf16 v[56:59], v[160:163], v[168:171], v[56:59]
	v_mfma_f32_16x16x32_bf16 v[44:47], v[152:155], v[176:179], v[44:47]
	v_mfma_f32_16x16x32_bf16 v[40:43], v[160:163], v[176:179], v[40:43]
	v_mfma_f32_16x16x32_bf16 v[28:31], v[152:155], v[184:187], v[28:31]
	v_mfma_f32_16x16x32_bf16 v[24:27], v[160:163], v[184:187], v[24:27]
	v_mfma_f32_16x16x32_bf16 v[12:15], v[152:155], v[192:195], v[12:15]
	v_mfma_f32_16x16x32_bf16 v[8:11], v[160:163], v[192:195], v[8:11]
	v_mfma_f32_16x16x32_bf16 v[60:63], v[156:159], v[172:175], v[60:63]
	v_mfma_f32_16x16x32_bf16 v[56:59], v[164:167], v[172:175], v[56:59]
	v_mfma_f32_16x16x32_bf16 v[44:47], v[156:159], v[180:183], v[44:47]
	v_mfma_f32_16x16x32_bf16 v[40:43], v[164:167], v[180:183], v[40:43]
	v_mfma_f32_16x16x32_bf16 v[28:31], v[156:159], v[188:191], v[28:31]
	v_mfma_f32_16x16x32_bf16 v[24:27], v[164:167], v[188:191], v[24:27]
	v_mfma_f32_16x16x32_bf16 v[12:15], v[156:159], v[196:199], v[12:15]
	v_mfma_f32_16x16x32_bf16 v[8:11], v[164:167], v[196:199], v[8:11]
	s_setprio 0
	s_barrier
	s_add_u32 s26, s26, 0x40080
	s_addc_u32 s27, s27, 0
	s_add_i32 s28, s28, s38
	s_mov_b32 m0, s28
	s_nop 0
	global_load_lds_dwordx4 v132, s[26:27]
	s_add_i32 m0, s28, 0x2000
	s_nop 0
	global_load_lds_dwordx4 v128, s[26:27]
	s_waitcnt vmcnt(6)
	s_barrier
	s_setprio 1
	v_mfma_f32_16x16x32_bf16 v[52:55], v[200:203], v[168:171], v[52:55]
	v_mfma_f32_16x16x32_bf16 v[48:51], v[208:211], v[168:171], v[48:51]
	v_mfma_f32_16x16x32_bf16 v[36:39], v[200:203], v[176:179], v[36:39]
	v_mfma_f32_16x16x32_bf16 v[32:35], v[208:211], v[176:179], v[32:35]
	v_mfma_f32_16x16x32_bf16 v[20:23], v[200:203], v[184:187], v[20:23]
	v_mfma_f32_16x16x32_bf16 v[16:19], v[208:211], v[184:187], v[16:19]
	v_mfma_f32_16x16x32_bf16 v[4:7], v[200:203], v[192:195], v[4:7]
	v_mfma_f32_16x16x32_bf16 v[0:3], v[208:211], v[192:195], v[0:3]
	v_mfma_f32_16x16x32_bf16 v[52:55], v[204:207], v[172:175], v[52:55]
	v_mfma_f32_16x16x32_bf16 v[48:51], v[212:215], v[172:175], v[48:51]
	v_mfma_f32_16x16x32_bf16 v[36:39], v[204:207], v[180:183], v[36:39]
	v_mfma_f32_16x16x32_bf16 v[32:35], v[212:215], v[180:183], v[32:35]
	v_mfma_f32_16x16x32_bf16 v[20:23], v[204:207], v[188:191], v[20:23]
	v_mfma_f32_16x16x32_bf16 v[16:19], v[212:215], v[188:191], v[16:19]
	v_mfma_f32_16x16x32_bf16 v[4:7], v[204:207], v[196:199], v[4:7]
	v_mfma_f32_16x16x32_bf16 v[0:3], v[212:215], v[196:199], v[0:3]
	s_setprio 0
	s_add_i32 s57, s57, 2
	s_add_u32 s20, s20, 0x100
	s_addc_u32 s21, s21, 0
	s_add_u32 s55, s55, 0x100
	s_addc_u32 s56, s56, 0
	s_cmp_gt_u32 s57, 13
	s_barrier
	s_cbranch_scc0 .LBB0_131
	s_cmpk_gt_u32 s37, 0xff
	s_cbranch_scc1 .Lg131_nox
	s_barrier

.LBB0_247:
	s_add_u32 s57, s26, 0x100
	s_addc_u32 s58, s27, 0
	s_mov_b32 s59, -2
	s_waitcnt lgkmcnt(0)
	s_cmpk_lt_u32 s35, 0x100
	s_cbranch_scc1 .Lg248_noy
	s_barrier
.Lg248_noy:
	ds_read_b128 v[144:147], v151
	ds_read_b128 v[156:159], v151 offset:1024
	ds_read_b128 v[160:163], v151 offset:2048
	ds_read_b128 v[164:167], v151 offset:3072
	s_add_u32 s26, s20, 0x100
	s_addc_u32 s27, s21, 0
	s_cmp_eq_u32 s59, 40
	s_cselect_b32 s31, s9, s27
	s_cselect_b32 s30, s8, s26
	s_cselect_b32 s29, s11, s58
	s_cselect_b32 s28, s10, s57
	s_add_i32 m0, s41, 0xc000
	ds_read_b128 v[168:171], v152
	ds_read_b128 v[172:175], v152 offset:1024
	ds_read_b128 v[176:179], v152 offset:2048
	ds_read_b128 v[180:183], v152 offset:3072
	ds_read_b128 v[184:187], v152 offset:4096
	ds_read_b128 v[188:191], v152 offset:5120
	ds_read_b128 v[192:195], v152 offset:6144
	ds_read_b128 v[196:199], v152 offset:7168
	global_load_lds_dwordx4 v136, s[20:21]
	s_add_i32 m0, s41, 0xe000
	s_nop 0
	global_load_lds_dwordx4 v138, s[20:21]
	s_waitcnt lgkmcnt(8)
	s_barrier
	s_waitcnt lgkmcnt(0)
	s_setprio 1
	s_waitcnt lgkmcnt(0)
	v_mfma_f32_16x16x32_bf16 v[124:127], v[144:147], v[168:171], 0
	v_mfma_f32_16x16x32_bf16 v[120:123], v[160:163], v[168:171], 0
	v_mfma_f32_16x16x32_bf16 v[108:111], v[144:147], v[176:179], 0
	v_mfma_f32_16x16x32_bf16 v[104:107], v[160:163], v[176:179], 0
	v_mfma_f32_16x16x32_bf16 v[92:95], v[144:147], v[184:187], 0
	v_mfma_f32_16x16x32_bf16 v[88:91], v[160:163], v[184:187], 0
	v_mfma_f32_16x16x32_bf16 v[76:79], v[144:147], v[192:195], 0
	v_mfma_f32_16x16x32_bf16 v[72:75], v[160:163], v[192:195], 0
	v_mfma_f32_16x16x32_bf16 v[124:127], v[156:159], v[172:175], v[124:127]
	v_mfma_f32_16x16x32_bf16 v[120:123], v[164:167], v[172:175], v[120:123]
	v_mfma_f32_16x16x32_bf16 v[108:111], v[156:159], v[180:183], v[108:111]
	v_mfma_f32_16x16x32_bf16 v[104:107], v[164:167], v[180:183], v[104:107]
	v_mfma_f32_16x16x32_bf16 v[92:95], v[156:159], v[188:191], v[92:95]
	v_mfma_f32_16x16x32_bf16 v[88:91], v[164:167], v[188:191], v[88:91]
	v_mfma_f32_16x16x32_bf16 v[76:79], v[156:159], v[196:199], v[76:79]
	v_mfma_f32_16x16x32_bf16 v[72:75], v[164:167], v[196:199], v[72:75]
	s_setprio 0
	s_barrier
	s_add_i32 s20, s51, s40
	s_add_u32 s80, s28, 0x80
	s_addc_u32 s81, s29, 0
	s_mov_b32 m0, s20
	ds_read_b128 v[200:203], v153
	ds_read_b128 v[204:207], v153 offset:1024
	ds_read_b128 v[208:211], v153 offset:2048
	ds_read_b128 v[212:215], v153 offset:3072
	global_load_lds_dwordx4 v130, s[28:29]
	s_add_i32 m0, s20, 0x2000
	s_nop 0
	global_load_lds_dwordx4 v134, s[28:29]
	s_barrier
	s_waitcnt lgkmcnt(0)
	s_setprio 1
	s_waitcnt lgkmcnt(0)
	v_mfma_f32_16x16x32_bf16 v[116:119], v[200:203], v[168:171], 0
	v_mfma_f32_16x16x32_bf16 v[112:115], v[208:211], v[168:171], 0
	v_mfma_f32_16x16x32_bf16 v[100:103], v[200:203], v[176:179], 0
	v_mfma_f32_16x16x32_bf16 v[96:99], v[208:211], v[176:179], 0
	v_mfma_f32_16x16x32_bf16 v[84:87], v[200:203], v[184:187], 0
	v_mfma_f32_16x16x32_bf16 v[80:83], v[208:211], v[184:187], 0
	v_mfma_f32_16x16x32_bf16 v[68:71], v[200:203], v[192:195], 0
	v_mfma_f32_16x16x32_bf16 v[64:67], v[208:211], v[192:195], 0
	v_mfma_f32_16x16x32_bf16 v[116:119], v[204:207], v[172:175], v[116:119]
	v_mfma_f32_16x16x32_bf16 v[112:115], v[212:215], v[172:175], v[112:115]
	v_mfma_f32_16x16x32_bf16 v[100:103], v[204:207], v[180:183], v[100:103]
	v_mfma_f32_16x16x32_bf16 v[96:99], v[212:215], v[180:183], v[96:99]
	v_mfma_f32_16x16x32_bf16 v[84:87], v[204:207], v[188:191], v[84:87]
	v_mfma_f32_16x16x32_bf16 v[80:83], v[212:215], v[188:191], v[80:83]
	v_mfma_f32_16x16x32_bf16 v[68:71], v[204:207], v[196:199], v[68:71]
	v_mfma_f32_16x16x32_bf16 v[64:67], v[212:215], v[196:199], v[64:67]
	s_setprio 0
	s_mov_b32 m0, s41
	s_add_u32 s82, s30, 0x80
	s_addc_u32 s83, s31, 0
	s_barrier
	ds_read_b128 v[168:171], v152 offset:16384
	ds_read_b128 v[172:175], v152 offset:17408
	ds_read_b128 v[176:179], v152 offset:18432
	ds_read_b128 v[180:183], v152 offset:19456
	ds_read_b128 v[184:187], v152 offset:20480
	ds_read_b128 v[188:191], v152 offset:21504
	ds_read_b128 v[192:195], v152 offset:22528
	ds_read_b128 v[196:199], v152 offset:23552
	global_load_lds_dwordx4 v128, s[30:31]
	s_mov_b32 m0, s42
	s_nop 0
	global_load_lds_dwordx4 v132, s[30:31]
	s_barrier
	s_waitcnt lgkmcnt(0)
	s_setprio 1
	s_waitcnt lgkmcnt(0)
	v_mfma_f32_16x16x32_bf16 v[60:63], v[144:147], v[168:171], 0
	v_mfma_f32_16x16x32_bf16 v[56:59], v[160:163], v[168:171], 0
	v_mfma_f32_16x16x32_bf16 v[44:47], v[144:147], v[176:179], 0
	v_mfma_f32_16x16x32_bf16 v[40:43], v[160:163], v[176:179], 0
	v_mfma_f32_16x16x32_bf16 v[28:31], v[144:147], v[184:187], 0
	v_mfma_f32_16x16x32_bf16 v[24:27], v[160:163], v[184:187], 0
	v_mfma_f32_16x16x32_bf16 v[12:15], v[144:147], v[192:195], 0
	v_mfma_f32_16x16x32_bf16 v[8:11], v[160:163], v[192:195], 0
	v_mfma_f32_16x16x32_bf16 v[60:63], v[156:159], v[172:175], v[60:63]
	v_mfma_f32_16x16x32_bf16 v[56:59], v[164:167], v[172:175], v[56:59]
	v_mfma_f32_16x16x32_bf16 v[44:47], v[156:159], v[180:183], v[44:47]
	v_mfma_f32_16x16x32_bf16 v[40:43], v[164:167], v[180:183], v[40:43]
	v_mfma_f32_16x16x32_bf16 v[28:31], v[156:159], v[188:191], v[28:31]
	v_mfma_f32_16x16x32_bf16 v[24:27], v[164:167], v[188:191], v[24:27]
	v_mfma_f32_16x16x32_bf16 v[12:15], v[156:159], v[196:199], v[12:15]
	v_mfma_f32_16x16x32_bf16 v[8:11], v[164:167], v[196:199], v[8:11]
	s_setprio 0
	s_barrier
	s_add_u32 s20, s28, 0xb0000
	s_addc_u32 s21, s29, 0
	s_add_i32 s60, s52, s40
	s_mov_b32 m0, s60
	s_nop 0
	global_load_lds_dwordx4 v130, s[20:21]
	s_add_i32 m0, s60, 0x2000
	s_nop 0
	global_load_lds_dwordx4 v134, s[20:21]
	s_waitcnt vmcnt(6)
	s_barrier
	s_setprio 1
	v_mfma_f32_16x16x32_bf16 v[52:55], v[200:203], v[168:171], 0
	v_mfma_f32_16x16x32_bf16 v[48:51], v[208:211], v[168:171], 0
	v_mfma_f32_16x16x32_bf16 v[36:39], v[200:203], v[176:179], 0
	v_mfma_f32_16x16x32_bf16 v[32:35], v[208:211], v[176:179], 0
	v_mfma_f32_16x16x32_bf16 v[20:23], v[200:203], v[184:187], 0
	v_mfma_f32_16x16x32_bf16 v[16:19], v[208:211], v[184:187], 0
	v_mfma_f32_16x16x32_bf16 v[4:7], v[200:203], v[192:195], 0
	v_mfma_f32_16x16x32_bf16 v[0:3], v[208:211], v[192:195], 0
	v_mfma_f32_16x16x32_bf16 v[52:55], v[204:207], v[172:175], v[52:55]
	v_mfma_f32_16x16x32_bf16 v[48:51], v[212:215], v[172:175], v[48:51]
	v_mfma_f32_16x16x32_bf16 v[36:39], v[204:207], v[180:183], v[36:39]
	v_mfma_f32_16x16x32_bf16 v[32:35], v[212:215], v[180:183], v[32:35]
	v_mfma_f32_16x16x32_bf16 v[20:23], v[204:207], v[188:191], v[20:23]
	v_mfma_f32_16x16x32_bf16 v[16:19], v[212:215], v[188:191], v[16:19]
	v_mfma_f32_16x16x32_bf16 v[4:7], v[204:207], v[196:199], v[4:7]
	v_mfma_f32_16x16x32_bf16 v[0:3], v[212:215], v[196:199], v[0:3]
	s_setprio 0
	s_add_i32 s60, 0, 0x18000
	v_add_u32_e32 v155, s60, v149
	s_barrier
	s_branch .Lg248_mid

.Lg248_mid:
	ds_read_b128 v[144:147], v155
	ds_read_b128 v[156:159], v155 offset:1024
	ds_read_b128 v[160:163], v155 offset:2048
	ds_read_b128 v[164:167], v155 offset:3072
	s_add_u32 s20, s30, 0xb0000
	s_addc_u32 s21, s31, 0
	s_mov_b32 m0, s43
	ds_read_b128 v[168:171], v152 offset:32768
	ds_read_b128 v[172:175], v152 offset:33792
	ds_read_b128 v[176:179], v152 offset:34816
	ds_read_b128 v[180:183], v152 offset:35840
	ds_read_b128 v[184:187], v152 offset:36864
	ds_read_b128 v[188:191], v152 offset:37888
	ds_read_b128 v[192:195], v152 offset:38912
	ds_read_b128 v[196:199], v152 offset:39936
	global_load_lds_dwordx4 v128, s[20:21]
	s_mov_b32 m0, s44
	s_nop 0
	global_load_lds_dwordx4 v132, s[20:21]
	s_waitcnt lgkmcnt(8)
	s_barrier
	s_waitcnt lgkmcnt(0)
	s_setprio 1
	s_waitcnt lgkmcnt(0)
	v_mfma_f32_16x16x32_bf16 v[124:127], v[144:147], v[168:171], v[124:127]
	v_mfma_f32_16x16x32_bf16 v[120:123], v[160:163], v[168:171], v[120:123]
	v_mfma_f32_16x16x32_bf16 v[108:111], v[144:147], v[176:179], v[108:111]
	v_mfma_f32_16x16x32_bf16 v[104:107], v[160:163], v[176:179], v[104:107]
	v_mfma_f32_16x16x32_bf16 v[92:95], v[144:147], v[184:187], v[92:95]
	v_mfma_f32_16x16x32_bf16 v[88:91], v[160:163], v[184:187], v[88:91]
	v_mfma_f32_16x16x32_bf16 v[76:79], v[144:147], v[192:195], v[76:79]
	v_mfma_f32_16x16x32_bf16 v[72:75], v[160:163], v[192:195], v[72:75]
	v_mfma_f32_16x16x32_bf16 v[124:127], v[156:159], v[172:175], v[124:127]
	v_mfma_f32_16x16x32_bf16 v[120:123], v[164:167], v[172:175], v[120:123]
	v_mfma_f32_16x16x32_bf16 v[108:111], v[156:159], v[180:183], v[108:111]
	v_mfma_f32_16x16x32_bf16 v[104:107], v[164:167], v[180:183], v[104:107]
	v_mfma_f32_16x16x32_bf16 v[92:95], v[156:159], v[188:191], v[92:95]
	v_mfma_f32_16x16x32_bf16 v[88:91], v[164:167], v[188:191], v[88:91]
	v_mfma_f32_16x16x32_bf16 v[76:79], v[156:159], v[196:199], v[76:79]
	v_mfma_f32_16x16x32_bf16 v[72:75], v[164:167], v[196:199], v[72:75]
	s_setprio 0
	s_barrier
	s_add_i32 s30, 0, 0x1c000
	s_add_i32 s20, s60, s40
	v_add_u32_e32 v155, s30, v149
	s_mov_b32 m0, s20
	ds_read_b128 v[200:203], v155
	ds_read_b128 v[204:207], v155 offset:1024
	ds_read_b128 v[208:211], v155 offset:2048
	ds_read_b128 v[212:215], v155 offset:3072
	global_load_lds_dwordx4 v130, s[80:81]
	s_add_i32 m0, s20, 0x2000
	s_nop 0
	global_load_lds_dwordx4 v134, s[80:81]
	s_barrier
	s_waitcnt lgkmcnt(0)
	s_setprio 1
	s_waitcnt lgkmcnt(0)
	v_mfma_f32_16x16x32_bf16 v[116:119], v[200:203], v[168:171], v[116:119]
	v_mfma_f32_16x16x32_bf16 v[112:115], v[208:211], v[168:171], v[112:115]
	v_mfma_f32_16x16x32_bf16 v[100:103], v[200:203], v[176:179], v[100:103]
	v_mfma_f32_16x16x32_bf16 v[96:99], v[208:211], v[176:179], v[96:99]
	v_mfma_f32_16x16x32_bf16 v[84:87], v[200:203], v[184:187], v[84:87]
	v_mfma_f32_16x16x32_bf16 v[80:83], v[208:211], v[184:187], v[80:83]
	v_mfma_f32_16x16x32_bf16 v[68:71], v[200:203], v[192:195], v[68:71]
	v_mfma_f32_16x16x32_bf16 v[64:67], v[208:211], v[192:195], v[64:67]
	v_mfma_f32_16x16x32_bf16 v[116:119], v[204:207], v[172:175], v[116:119]
	v_mfma_f32_16x16x32_bf16 v[112:115], v[212:215], v[172:175], v[112:115]
	v_mfma_f32_16x16x32_bf16 v[100:103], v[204:207], v[180:183], v[100:103]
	v_mfma_f32_16x16x32_bf16 v[96:99], v[212:215], v[180:183], v[96:99]
	v_mfma_f32_16x16x32_bf16 v[84:87], v[204:207], v[188:191], v[84:87]
	v_mfma_f32_16x16x32_bf16 v[80:83], v[212:215], v[188:191], v[80:83]
	v_mfma_f32_16x16x32_bf16 v[68:71], v[204:207], v[196:199], v[68:71]
	v_mfma_f32_16x16x32_bf16 v[64:67], v[212:215], v[196:199], v[64:67]
	s_setprio 0
	s_mov_b32 m0, s46
	s_barrier
	ds_read_b128 v[168:171], v152 offset:49152
	ds_read_b128 v[172:175], v152 offset:50176
	ds_read_b128 v[176:179], v152 offset:51200
	ds_read_b128 v[180:183], v152 offset:52224
	ds_read_b128 v[184:187], v152 offset:53248
	ds_read_b128 v[188:191], v152 offset:54272
	ds_read_b128 v[192:195], v152 offset:55296
	ds_read_b128 v[196:199], v152 offset:56320
	global_load_lds_dwordx4 v128, s[82:83]
	s_mov_b32 m0, s47
	s_nop 0
	global_load_lds_dwordx4 v132, s[82:83]
	s_barrier
	s_waitcnt lgkmcnt(0)
	s_setprio 1
	s_waitcnt lgkmcnt(0)
	v_mfma_f32_16x16x32_bf16 v[60:63], v[144:147], v[168:171], v[60:63]
	v_mfma_f32_16x16x32_bf16 v[56:59], v[160:163], v[168:171], v[56:59]
	v_mfma_f32_16x16x32_bf16 v[44:47], v[144:147], v[176:179], v[44:47]
	v_mfma_f32_16x16x32_bf16 v[40:43], v[160:163], v[176:179], v[40:43]
	v_mfma_f32_16x16x32_bf16 v[28:31], v[144:147], v[184:187], v[28:31]
	v_mfma_f32_16x16x32_bf16 v[24:27], v[160:163], v[184:187], v[24:27]
	v_mfma_f32_16x16x32_bf16 v[12:15], v[144:147], v[192:195], v[12:15]
	v_mfma_f32_16x16x32_bf16 v[8:11], v[160:163], v[192:195], v[8:11]
	v_mfma_f32_16x16x32_bf16 v[60:63], v[156:159], v[172:175], v[60:63]
	v_mfma_f32_16x16x32_bf16 v[56:59], v[164:167], v[172:175], v[56:59]
	v_mfma_f32_16x16x32_bf16 v[44:47], v[156:159], v[180:183], v[44:47]
	v_mfma_f32_16x16x32_bf16 v[40:43], v[164:167], v[180:183], v[40:43]
	v_mfma_f32_16x16x32_bf16 v[28:31], v[156:159], v[188:191], v[28:31]
	v_mfma_f32_16x16x32_bf16 v[24:27], v[164:167], v[188:191], v[24:27]
	v_mfma_f32_16x16x32_bf16 v[12:15], v[156:159], v[196:199], v[12:15]
	v_mfma_f32_16x16x32_bf16 v[8:11], v[164:167], v[196:199], v[8:11]
	s_setprio 0
	s_barrier
	s_add_u32 s20, s28, 0xb0080
	s_addc_u32 s21, s29, 0
	s_add_i32 s28, s30, s40
	s_mov_b32 m0, s28
	s_nop 0
	global_load_lds_dwordx4 v130, s[20:21]
	s_add_i32 m0, s28, 0x2000
	s_nop 0
	global_load_lds_dwordx4 v134, s[20:21]
	s_waitcnt vmcnt(6)
	s_barrier
	s_setprio 1
	v_mfma_f32_16x16x32_bf16 v[52:55], v[200:203], v[168:171], v[52:55]
	v_mfma_f32_16x16x32_bf16 v[48:51], v[208:211], v[168:171], v[48:51]
	v_mfma_f32_16x16x32_bf16 v[36:39], v[200:203], v[176:179], v[36:39]
	v_mfma_f32_16x16x32_bf16 v[32:35], v[208:211], v[176:179], v[32:35]
	v_mfma_f32_16x16x32_bf16 v[20:23], v[200:203], v[184:187], v[20:23]
	v_mfma_f32_16x16x32_bf16 v[16:19], v[208:211], v[184:187], v[16:19]
	v_mfma_f32_16x16x32_bf16 v[4:7], v[200:203], v[192:195], v[4:7]
	v_mfma_f32_16x16x32_bf16 v[0:3], v[208:211], v[192:195], v[0:3]
	v_mfma_f32_16x16x32_bf16 v[52:55], v[204:207], v[172:175], v[52:55]
	v_mfma_f32_16x16x32_bf16 v[48:51], v[212:215], v[172:175], v[48:51]
	v_mfma_f32_16x16x32_bf16 v[36:39], v[204:207], v[180:183], v[36:39]
	v_mfma_f32_16x16x32_bf16 v[32:35], v[212:215], v[180:183], v[32:35]
	v_mfma_f32_16x16x32_bf16 v[20:23], v[204:207], v[188:191], v[20:23]
	v_mfma_f32_16x16x32_bf16 v[16:19], v[212:215], v[188:191], v[16:19]
	v_mfma_f32_16x16x32_bf16 v[4:7], v[204:207], v[196:199], v[4:7]
	v_mfma_f32_16x16x32_bf16 v[0:3], v[212:215], v[196:199], v[0:3]
	s_setprio 0
	s_add_i32 s59, s59, 2
	s_add_u32 s57, s57, 0x100
	s_addc_u32 s58, s58, 0
	s_cmp_gt_u32 s59, 41
	s_mov_b64 s[20:21], s[26:27]
	s_barrier
	s_cbranch_scc0 .LBB0_248
	v_lshl_add_u32 v146, s56, 8, v148
	v_ashrrev_i32_e32 v147, 31, v146
	v_lshl_or_b32 v144, s12, 8, v150
	v_lshlrev_b64 v[156:157], 11, v[146:147]
	v_ashrrev_i32_e32 v145, 31, v144
	v_lshl_add_u64 v[156:157], s[14:15], 0, v[156:157]
	v_lshl_add_u64 v[166:167], v[144:145], 1, v[156:157]
	global_load_dwordx4 v[158:161], v[166:167], off
	global_load_dwordx4 v[162:165], v[166:167], off offset:256
	s_mov_b64 s[84:85], 0x8000
	s_mov_b64 s[86:87], 0x28000
	v_lshl_add_u64 v[232:233], v[166:167], 0, s[84:85]
	global_load_dwordx4 v[176:179], v[232:233], off
	global_load_dwordx4 v[180:183], v[232:233], off offset:256
	v_lshl_add_u64 v[232:233], v[232:233], 0, s[84:85]
	global_load_dwordx4 v[184:187], v[232:233], off
	global_load_dwordx4 v[188:191], v[232:233], off offset:256
	v_lshl_add_u64 v[232:233], v[232:233], 0, s[84:85]
	global_load_dwordx4 v[192:195], v[232:233], off
	global_load_dwordx4 v[196:199], v[232:233], off offset:256
	v_lshl_add_u64 v[232:233], v[232:233], 0, s[86:87]
	global_load_dwordx4 v[200:203], v[232:233], off
	global_load_dwordx4 v[204:207], v[232:233], off offset:256
	v_lshl_add_u64 v[232:233], v[232:233], 0, s[84:85]
	global_load_dwordx4 v[208:211], v[232:233], off
	global_load_dwordx4 v[212:215], v[232:233], off offset:256
	v_lshl_add_u64 v[232:233], v[232:233], 0, s[84:85]
	global_load_dwordx4 v[216:219], v[232:233], off
	global_load_dwordx4 v[220:223], v[232:233], off offset:256
	v_lshl_add_u64 v[232:233], v[232:233], 0, s[84:85]
	global_load_dwordx4 v[224:227], v[232:233], off
	global_load_dwordx4 v[228:231], v[232:233], off offset:256
	s_cmpk_gt_u32 s35, 0xff
	s_cbranch_scc1 .Lg248_nox
	s_barrier

.LBB0_358:
	s_ashr_i32 s21, s20, 31
	v_cmp_lt_i64_e32 vcc, s[30:31], v[162:163]
	s_lshl_b64 s[30:31], s[20:21], 19
	s_add_u32 s30, s47, s30
	s_addc_u32 s31, s48, s31
	s_and_b64 s[34:35], vcc, exec
	s_cselect_b32 s21, s31, s9
	s_cselect_b32 s71, s30, s8
	s_ashr_i32 s19, s18, 31
	s_lshl_b64 s[34:35], s[18:19], 19
	s_add_u32 s34, s49, s34
	s_addc_u32 s35, s50, s35
	s_and_b64 s[40:41], vcc, exec
	s_cselect_b32 s19, s35, s39
	s_cselect_b32 s72, s34, s38
	s_add_u32 s8, s8, 0x40080
	s_addc_u32 s9, s9, 0
	s_add_u32 s73, s38, 0x100
	s_addc_u32 s74, s39, 0
	s_mov_b32 s75, -2
	s_cmpk_lt_u32 s45, 0x100
	s_cbranch_scc1 .Lg359_noy
	s_barrier
.Lg359_noy:
	ds_read_b128 v[128:131], v181
	ds_read_b128 v[132:135], v181 offset:1024
	ds_read_b128 v[136:139], v181 offset:2048
	ds_read_b128 v[166:169], v181 offset:3072
	s_add_u32 s38, s8, 0xfffc0080
	s_addc_u32 s39, s9, -1
	s_cmp_eq_u32 s75, 12
	s_cselect_b32 s41, s21, s39
	s_cselect_b32 s40, s71, s38
	s_cselect_b32 s39, s19, s74
	s_cselect_b32 s38, s72, s73
	s_add_i32 m0, s37, 0xc000
	ds_read_b128 v[170:173], v182
	ds_read_b128 v[174:177], v182 offset:1024
	ds_read_b128 v[192:195], v182 offset:2048
	ds_read_b128 v[196:199], v182 offset:3072
	ds_read_b128 v[200:203], v182 offset:4096
	ds_read_b128 v[204:207], v182 offset:5120
	ds_read_b128 v[208:211], v182 offset:6144
	ds_read_b128 v[212:215], v182 offset:7168
	global_load_lds_dwordx4 v158, s[8:9]
	s_add_i32 m0, s37, 0xe000
	s_nop 0
	global_load_lds_dwordx4 v160, s[8:9]
	s_waitcnt lgkmcnt(8)
	s_barrier
	s_waitcnt lgkmcnt(0)
	s_setprio 1
	s_waitcnt lgkmcnt(0)
	v_mfma_f32_16x16x32_bf16 v[124:127], v[128:131], v[170:173], 0
	v_mfma_f32_16x16x32_bf16 v[116:119], v[136:139], v[170:173], 0
	v_mfma_f32_16x16x32_bf16 v[108:111], v[128:131], v[192:195], 0
	v_mfma_f32_16x16x32_bf16 v[100:103], v[136:139], v[192:195], 0
	v_mfma_f32_16x16x32_bf16 v[92:95], v[128:131], v[200:203], 0
	v_mfma_f32_16x16x32_bf16 v[84:87], v[136:139], v[200:203], 0
	v_mfma_f32_16x16x32_bf16 v[76:79], v[128:131], v[208:211], 0
	v_mfma_f32_16x16x32_bf16 v[68:71], v[136:139], v[208:211], 0
	v_mfma_f32_16x16x32_bf16 v[124:127], v[132:135], v[174:177], v[124:127]
	v_mfma_f32_16x16x32_bf16 v[116:119], v[166:169], v[174:177], v[116:119]
	v_mfma_f32_16x16x32_bf16 v[108:111], v[132:135], v[196:199], v[108:111]
	v_mfma_f32_16x16x32_bf16 v[100:103], v[166:169], v[196:199], v[100:103]
	v_mfma_f32_16x16x32_bf16 v[92:95], v[132:135], v[204:207], v[92:95]
	v_mfma_f32_16x16x32_bf16 v[84:87], v[166:169], v[204:207], v[84:87]
	v_mfma_f32_16x16x32_bf16 v[76:79], v[132:135], v[212:215], v[76:79]
	v_mfma_f32_16x16x32_bf16 v[68:71], v[166:169], v[212:215], v[68:71]
	s_setprio 0
	s_barrier
	s_add_i32 s76, s63, s46
	s_add_u32 s80, s38, 0x80
	s_addc_u32 s81, s39, 0
	s_mov_b32 m0, s76
	ds_read_b128 v[216:219], v183
	ds_read_b128 v[220:223], v183 offset:1024
	ds_read_b128 v[224:227], v183 offset:2048
	ds_read_b128 v[228:231], v183 offset:3072
	global_load_lds_dwordx4 v144, s[38:39]
	s_add_i32 m0, s76, 0x2000
	s_nop 0
	global_load_lds_dwordx4 v148, s[38:39]
	s_barrier
	s_waitcnt lgkmcnt(0)
	s_setprio 1
	s_waitcnt lgkmcnt(0)
	v_mfma_f32_16x16x32_bf16 v[120:123], v[216:219], v[170:173], 0
	v_mfma_f32_16x16x32_bf16 v[112:115], v[224:227], v[170:173], 0
	v_mfma_f32_16x16x32_bf16 v[104:107], v[216:219], v[192:195], 0
	v_mfma_f32_16x16x32_bf16 v[96:99], v[224:227], v[192:195], 0
	v_mfma_f32_16x16x32_bf16 v[88:91], v[216:219], v[200:203], 0
	v_mfma_f32_16x16x32_bf16 v[80:83], v[224:227], v[200:203], 0
	v_mfma_f32_16x16x32_bf16 v[72:75], v[216:219], v[208:211], 0
	v_mfma_f32_16x16x32_bf16 v[64:67], v[224:227], v[208:211], 0
	v_mfma_f32_16x16x32_bf16 v[120:123], v[220:223], v[174:177], v[120:123]
	v_mfma_f32_16x16x32_bf16 v[112:115], v[228:231], v[174:177], v[112:115]
	v_mfma_f32_16x16x32_bf16 v[104:107], v[220:223], v[196:199], v[104:107]
	v_mfma_f32_16x16x32_bf16 v[96:99], v[228:231], v[196:199], v[96:99]
	v_mfma_f32_16x16x32_bf16 v[88:91], v[220:223], v[204:207], v[88:91]
	v_mfma_f32_16x16x32_bf16 v[80:83], v[228:231], v[204:207], v[80:83]
	v_mfma_f32_16x16x32_bf16 v[72:75], v[220:223], v[212:215], v[72:75]
	v_mfma_f32_16x16x32_bf16 v[64:67], v[228:231], v[212:215], v[64:67]
	s_setprio 0
	s_mov_b32 m0, s37
	s_add_u32 s82, s40, 0x80
	s_addc_u32 s83, s41, 0
	s_barrier
	ds_read_b128 v[170:173], v182 offset:16384
	ds_read_b128 v[174:177], v182 offset:17408
	ds_read_b128 v[192:195], v182 offset:18432
	ds_read_b128 v[196:199], v182 offset:19456
	ds_read_b128 v[200:203], v182 offset:20480
	ds_read_b128 v[204:207], v182 offset:21504
	ds_read_b128 v[208:211], v182 offset:22528
	ds_read_b128 v[212:215], v182 offset:23552
	global_load_lds_dwordx4 v142, s[40:41]
	s_mov_b32 m0, s51
	s_nop 0
	global_load_lds_dwordx4 v146, s[40:41]
	s_barrier
	s_waitcnt lgkmcnt(0)
	s_setprio 1
	s_waitcnt lgkmcnt(0)
	v_mfma_f32_16x16x32_bf16 v[60:63], v[128:131], v[170:173], 0
	v_mfma_f32_16x16x32_bf16 v[52:55], v[136:139], v[170:173], 0
	v_mfma_f32_16x16x32_bf16 v[44:47], v[128:131], v[192:195], 0
	v_mfma_f32_16x16x32_bf16 v[36:39], v[136:139], v[192:195], 0
	v_mfma_f32_16x16x32_bf16 v[28:31], v[128:131], v[200:203], 0
	v_mfma_f32_16x16x32_bf16 v[20:23], v[136:139], v[200:203], 0
	v_mfma_f32_16x16x32_bf16 v[12:15], v[128:131], v[208:211], 0
	v_mfma_f32_16x16x32_bf16 v[4:7], v[136:139], v[208:211], 0
	v_mfma_f32_16x16x32_bf16 v[60:63], v[132:135], v[174:177], v[60:63]
	v_mfma_f32_16x16x32_bf16 v[52:55], v[166:169], v[174:177], v[52:55]
	v_mfma_f32_16x16x32_bf16 v[44:47], v[132:135], v[196:199], v[44:47]
	v_mfma_f32_16x16x32_bf16 v[36:39], v[166:169], v[196:199], v[36:39]
	v_mfma_f32_16x16x32_bf16 v[28:31], v[132:135], v[204:207], v[28:31]
	v_mfma_f32_16x16x32_bf16 v[20:23], v[166:169], v[204:207], v[20:23]
	v_mfma_f32_16x16x32_bf16 v[12:15], v[132:135], v[212:215], v[12:15]
	v_mfma_f32_16x16x32_bf16 v[4:7], v[166:169], v[212:215], v[4:7]
	s_setprio 0
	s_barrier
	s_add_u32 s76, s38, 0x40000
	s_addc_u32 s77, s39, 0
	s_add_i32 s78, s64, s46
	s_mov_b32 m0, s78
	s_nop 0
	global_load_lds_dwordx4 v144, s[76:77]
	s_add_i32 m0, s78, 0x2000
	s_nop 0
	global_load_lds_dwordx4 v148, s[76:77]
	s_waitcnt vmcnt(6)
	s_barrier
	s_setprio 1
	v_mfma_f32_16x16x32_bf16 v[56:59], v[216:219], v[170:173], 0
	v_mfma_f32_16x16x32_bf16 v[48:51], v[224:227], v[170:173], 0
	v_mfma_f32_16x16x32_bf16 v[40:43], v[216:219], v[192:195], 0
	v_mfma_f32_16x16x32_bf16 v[32:35], v[224:227], v[192:195], 0
	v_mfma_f32_16x16x32_bf16 v[24:27], v[216:219], v[200:203], 0
	v_mfma_f32_16x16x32_bf16 v[16:19], v[224:227], v[200:203], 0
	v_mfma_f32_16x16x32_bf16 v[8:11], v[216:219], v[208:211], 0
	v_mfma_f32_16x16x32_bf16 v[0:3], v[224:227], v[208:211], 0
	v_mfma_f32_16x16x32_bf16 v[56:59], v[220:223], v[174:177], v[56:59]
	v_mfma_f32_16x16x32_bf16 v[48:51], v[228:231], v[174:177], v[48:51]
	v_mfma_f32_16x16x32_bf16 v[40:43], v[220:223], v[196:199], v[40:43]
	v_mfma_f32_16x16x32_bf16 v[32:35], v[228:231], v[196:199], v[32:35]
	v_mfma_f32_16x16x32_bf16 v[24:27], v[220:223], v[204:207], v[24:27]
	v_mfma_f32_16x16x32_bf16 v[16:19], v[228:231], v[204:207], v[16:19]
	v_mfma_f32_16x16x32_bf16 v[8:11], v[220:223], v[212:215], v[8:11]
	v_mfma_f32_16x16x32_bf16 v[0:3], v[228:231], v[212:215], v[0:3]
	s_setprio 0
	s_add_i32 s76, 0, 0x18000
	v_add_u32_e32 v150, s76, v179
	s_barrier
	s_branch .Lg359_mid

.Lg359_mid:
	ds_read_b128 v[128:131], v150
	ds_read_b128 v[132:135], v150 offset:1024
	ds_read_b128 v[136:139], v150 offset:2048
	ds_read_b128 v[166:169], v150 offset:3072
	s_add_u32 s40, s40, 0x40000
	s_addc_u32 s41, s41, 0
	s_mov_b32 m0, s52
	ds_read_b128 v[170:173], v182 offset:32768
	ds_read_b128 v[174:177], v182 offset:33792
	ds_read_b128 v[192:195], v182 offset:34816
	ds_read_b128 v[196:199], v182 offset:35840
	ds_read_b128 v[200:203], v182 offset:36864
	ds_read_b128 v[204:207], v182 offset:37888
	ds_read_b128 v[208:211], v182 offset:38912
	ds_read_b128 v[212:215], v182 offset:39936
	global_load_lds_dwordx4 v142, s[40:41]
	s_mov_b32 m0, s53
	s_nop 0
	global_load_lds_dwordx4 v146, s[40:41]
	s_waitcnt lgkmcnt(8)
	s_barrier
	s_waitcnt lgkmcnt(0)
	s_setprio 1
	s_waitcnt lgkmcnt(0)
	v_mfma_f32_16x16x32_bf16 v[124:127], v[128:131], v[170:173], v[124:127]
	v_mfma_f32_16x16x32_bf16 v[116:119], v[136:139], v[170:173], v[116:119]
	v_mfma_f32_16x16x32_bf16 v[108:111], v[128:131], v[192:195], v[108:111]
	v_mfma_f32_16x16x32_bf16 v[100:103], v[136:139], v[192:195], v[100:103]
	v_mfma_f32_16x16x32_bf16 v[92:95], v[128:131], v[200:203], v[92:95]
	v_mfma_f32_16x16x32_bf16 v[84:87], v[136:139], v[200:203], v[84:87]
	v_mfma_f32_16x16x32_bf16 v[76:79], v[128:131], v[208:211], v[76:79]
	v_mfma_f32_16x16x32_bf16 v[68:71], v[136:139], v[208:211], v[68:71]
	v_mfma_f32_16x16x32_bf16 v[124:127], v[132:135], v[174:177], v[124:127]
	v_mfma_f32_16x16x32_bf16 v[116:119], v[166:169], v[174:177], v[116:119]
	v_mfma_f32_16x16x32_bf16 v[108:111], v[132:135], v[196:199], v[108:111]
	v_mfma_f32_16x16x32_bf16 v[100:103], v[166:169], v[196:199], v[100:103]
	v_mfma_f32_16x16x32_bf16 v[92:95], v[132:135], v[204:207], v[92:95]
	v_mfma_f32_16x16x32_bf16 v[84:87], v[166:169], v[204:207], v[84:87]
	v_mfma_f32_16x16x32_bf16 v[76:79], v[132:135], v[212:215], v[76:79]
	v_mfma_f32_16x16x32_bf16 v[68:71], v[166:169], v[212:215], v[68:71]
	s_setprio 0
	s_barrier
	s_add_i32 s40, 0, 0x1c000
	s_add_i32 s41, s76, s46
	v_add_u32_e32 v150, s40, v179
	s_mov_b32 m0, s41
	ds_read_b128 v[216:219], v150
	ds_read_b128 v[220:223], v150 offset:1024
	ds_read_b128 v[224:227], v150 offset:2048
	ds_read_b128 v[228:231], v150 offset:3072
	global_load_lds_dwordx4 v144, s[80:81]
	s_add_i32 m0, s41, 0x2000
	s_nop 0
	global_load_lds_dwordx4 v148, s[80:81]
	s_barrier
	s_waitcnt lgkmcnt(0)
	s_setprio 1
	s_waitcnt lgkmcnt(0)
	v_mfma_f32_16x16x32_bf16 v[120:123], v[216:219], v[170:173], v[120:123]
	v_mfma_f32_16x16x32_bf16 v[112:115], v[224:227], v[170:173], v[112:115]
	v_mfma_f32_16x16x32_bf16 v[104:107], v[216:219], v[192:195], v[104:107]
	v_mfma_f32_16x16x32_bf16 v[96:99], v[224:227], v[192:195], v[96:99]
	v_mfma_f32_16x16x32_bf16 v[88:91], v[216:219], v[200:203], v[88:91]
	v_mfma_f32_16x16x32_bf16 v[80:83], v[224:227], v[200:203], v[80:83]
	v_mfma_f32_16x16x32_bf16 v[72:75], v[216:219], v[208:211], v[72:75]
	v_mfma_f32_16x16x32_bf16 v[64:67], v[224:227], v[208:211], v[64:67]
	v_mfma_f32_16x16x32_bf16 v[120:123], v[220:223], v[174:177], v[120:123]
	v_mfma_f32_16x16x32_bf16 v[112:115], v[228:231], v[174:177], v[112:115]
	v_mfma_f32_16x16x32_bf16 v[104:107], v[220:223], v[196:199], v[104:107]
	v_mfma_f32_16x16x32_bf16 v[96:99], v[228:231], v[196:199], v[96:99]
	v_mfma_f32_16x16x32_bf16 v[88:91], v[220:223], v[204:207], v[88:91]
	v_mfma_f32_16x16x32_bf16 v[80:83], v[228:231], v[204:207], v[80:83]
	v_mfma_f32_16x16x32_bf16 v[72:75], v[220:223], v[212:215], v[72:75]
	v_mfma_f32_16x16x32_bf16 v[64:67], v[228:231], v[212:215], v[64:67]
	s_setprio 0
	s_mov_b32 m0, s55
	s_barrier
	ds_read_b128 v[170:173], v182 offset:49152
	ds_read_b128 v[174:177], v182 offset:50176
	ds_read_b128 v[192:195], v182 offset:51200
	ds_read_b128 v[196:199], v182 offset:52224
	ds_read_b128 v[200:203], v182 offset:53248
	ds_read_b128 v[204:207], v182 offset:54272
	ds_read_b128 v[208:211], v182 offset:55296
	ds_read_b128 v[212:215], v182 offset:56320
	global_load_lds_dwordx4 v142, s[82:83]
	s_mov_b32 m0, s56
	s_nop 0
	global_load_lds_dwordx4 v146, s[82:83]
	s_barrier
	s_waitcnt lgkmcnt(0)
	s_setprio 1
	s_waitcnt lgkmcnt(0)
	v_mfma_f32_16x16x32_bf16 v[60:63], v[128:131], v[170:173], v[60:63]
	v_mfma_f32_16x16x32_bf16 v[52:55], v[136:139], v[170:173], v[52:55]
	v_mfma_f32_16x16x32_bf16 v[44:47], v[128:131], v[192:195], v[44:47]
	v_mfma_f32_16x16x32_bf16 v[36:39], v[136:139], v[192:195], v[36:39]
	v_mfma_f32_16x16x32_bf16 v[28:31], v[128:131], v[200:203], v[28:31]
	v_mfma_f32_16x16x32_bf16 v[20:23], v[136:139], v[200:203], v[20:23]
	v_mfma_f32_16x16x32_bf16 v[12:15], v[128:131], v[208:211], v[12:15]
	v_mfma_f32_16x16x32_bf16 v[4:7], v[136:139], v[208:211], v[4:7]
	v_mfma_f32_16x16x32_bf16 v[60:63], v[132:135], v[174:177], v[60:63]
	v_mfma_f32_16x16x32_bf16 v[52:55], v[166:169], v[174:177], v[52:55]
	v_mfma_f32_16x16x32_bf16 v[44:47], v[132:135], v[196:199], v[44:47]
	v_mfma_f32_16x16x32_bf16 v[36:39], v[166:169], v[196:199], v[36:39]
	v_mfma_f32_16x16x32_bf16 v[28:31], v[132:135], v[204:207], v[28:31]
	v_mfma_f32_16x16x32_bf16 v[20:23], v[166:169], v[204:207], v[20:23]
	v_mfma_f32_16x16x32_bf16 v[12:15], v[132:135], v[212:215], v[12:15]
	v_mfma_f32_16x16x32_bf16 v[4:7], v[166:169], v[212:215], v[4:7]
	s_setprio 0
	s_barrier
	s_add_u32 s38, s38, 0x40080
	s_addc_u32 s39, s39, 0
	s_add_i32 s40, s40, s46
	s_mov_b32 m0, s40
	s_nop 0
	global_load_lds_dwordx4 v144, s[38:39]
	s_add_i32 m0, s40, 0x2000
	s_nop 0
	global_load_lds_dwordx4 v148, s[38:39]
	s_waitcnt vmcnt(6)
	s_barrier
	s_setprio 1
	v_mfma_f32_16x16x32_bf16 v[56:59], v[216:219], v[170:173], v[56:59]
	v_mfma_f32_16x16x32_bf16 v[48:51], v[224:227], v[170:173], v[48:51]
	v_mfma_f32_16x16x32_bf16 v[40:43], v[216:219], v[192:195], v[40:43]
	v_mfma_f32_16x16x32_bf16 v[32:35], v[224:227], v[192:195], v[32:35]
	v_mfma_f32_16x16x32_bf16 v[24:27], v[216:219], v[200:203], v[24:27]
	v_mfma_f32_16x16x32_bf16 v[16:19], v[224:227], v[200:203], v[16:19]
	v_mfma_f32_16x16x32_bf16 v[8:11], v[216:219], v[208:211], v[8:11]
	v_mfma_f32_16x16x32_bf16 v[0:3], v[224:227], v[208:211], v[0:3]
	v_mfma_f32_16x16x32_bf16 v[56:59], v[220:223], v[174:177], v[56:59]
	v_mfma_f32_16x16x32_bf16 v[48:51], v[228:231], v[174:177], v[48:51]
	v_mfma_f32_16x16x32_bf16 v[40:43], v[220:223], v[196:199], v[40:43]
	v_mfma_f32_16x16x32_bf16 v[32:35], v[228:231], v[196:199], v[32:35]
	v_mfma_f32_16x16x32_bf16 v[24:27], v[220:223], v[204:207], v[24:27]
	v_mfma_f32_16x16x32_bf16 v[16:19], v[228:231], v[204:207], v[16:19]
	v_mfma_f32_16x16x32_bf16 v[8:11], v[220:223], v[212:215], v[8:11]
	v_mfma_f32_16x16x32_bf16 v[0:3], v[228:231], v[212:215], v[0:3]
	s_setprio 0
	s_add_i32 s75, s75, 2
	s_add_u32 s8, s8, 0x100
	s_addc_u32 s9, s9, 0
	s_add_u32 s73, s73, 0x100
	s_addc_u32 s74, s74, 0
	s_cmp_gt_u32 s75, 13
	s_barrier
	s_cbranch_scc0 .LBB0_359
	s_cmpk_gt_u32 s45, 0xff
	s_cbranch_scc1 .Lg359_nox
	s_barrier

.LBB0_785:
	s_ashr_i32 s19, s18, 31
	v_cmp_lt_i64_e32 vcc, s[20:21], v[140:141]
	s_lshl_b64 s[20:21], s[18:19], 19
	s_add_u32 s20, s38, s20
	s_addc_u32 s21, s39, s21
	s_and_b64 s[26:27], vcc, exec
	s_cselect_b32 s19, s21, s29
	s_cselect_b32 s57, s20, s28
	s_ashr_i32 s17, s16, 31
	s_lshl_b64 s[26:27], s[16:17], 19
	s_add_u32 s26, s40, s26
	s_addc_u32 s27, s41, s27
	s_and_b64 s[34:35], vcc, exec
	s_cselect_b32 s17, s27, s31
	s_cselect_b32 s58, s26, s30
	s_add_u32 s28, s28, 0x40080
	s_addc_u32 s29, s29, 0
	s_add_u32 s59, s30, 0x100
	s_addc_u32 s60, s31, 0
	s_mov_b32 s61, -2
	s_waitcnt lgkmcnt(0)
	s_cmpk_lt_u32 s37, 0x100
	s_cbranch_scc1 .Lg786_noy
	s_barrier
.Lg786_noy:
	ds_read_b128 v[144:147], v151
	ds_read_b128 v[156:159], v151 offset:1024
	ds_read_b128 v[160:163], v151 offset:2048
	ds_read_b128 v[164:167], v151 offset:3072
	s_add_u32 s30, s28, 0xfffc0080
	s_addc_u32 s31, s29, -1
	s_cmp_eq_u32 s61, 12
	s_cselect_b32 s35, s19, s31
	s_cselect_b32 s34, s57, s30
	s_cselect_b32 s31, s17, s60
	s_cselect_b32 s30, s58, s59
	s_add_i32 m0, s45, 0xc000
	ds_read_b128 v[168:171], v152
	ds_read_b128 v[172:175], v152 offset:1024
	ds_read_b128 v[176:179], v152 offset:2048
	ds_read_b128 v[180:183], v152 offset:3072
	ds_read_b128 v[184:187], v152 offset:4096
	ds_read_b128 v[188:191], v152 offset:5120
	ds_read_b128 v[192:195], v152 offset:6144
	ds_read_b128 v[196:199], v152 offset:7168
	global_load_lds_dwordx4 v136, s[28:29]
	s_add_i32 m0, s45, 0xe000
	s_nop 0
	global_load_lds_dwordx4 v138, s[28:29]
	s_waitcnt lgkmcnt(8)
	s_barrier
	s_waitcnt lgkmcnt(0)
	s_setprio 1
	s_waitcnt lgkmcnt(0)
	v_mfma_f32_16x16x32_bf16 v[124:127], v[144:147], v[168:171], 0
	v_mfma_f32_16x16x32_bf16 v[120:123], v[160:163], v[168:171], 0
	v_mfma_f32_16x16x32_bf16 v[108:111], v[144:147], v[176:179], 0
	v_mfma_f32_16x16x32_bf16 v[104:107], v[160:163], v[176:179], 0
	v_mfma_f32_16x16x32_bf16 v[92:95], v[144:147], v[184:187], 0
	v_mfma_f32_16x16x32_bf16 v[88:91], v[160:163], v[184:187], 0
	v_mfma_f32_16x16x32_bf16 v[76:79], v[144:147], v[192:195], 0
	v_mfma_f32_16x16x32_bf16 v[72:75], v[160:163], v[192:195], 0
	v_mfma_f32_16x16x32_bf16 v[124:127], v[156:159], v[172:175], v[124:127]
	v_mfma_f32_16x16x32_bf16 v[120:123], v[164:167], v[172:175], v[120:123]
	v_mfma_f32_16x16x32_bf16 v[108:111], v[156:159], v[180:183], v[108:111]
	v_mfma_f32_16x16x32_bf16 v[104:107], v[164:167], v[180:183], v[104:107]
	v_mfma_f32_16x16x32_bf16 v[92:95], v[156:159], v[188:191], v[92:95]
	v_mfma_f32_16x16x32_bf16 v[88:91], v[164:167], v[188:191], v[88:91]
	v_mfma_f32_16x16x32_bf16 v[76:79], v[156:159], v[196:199], v[76:79]
	v_mfma_f32_16x16x32_bf16 v[72:75], v[164:167], v[196:199], v[72:75]
	s_setprio 0
	s_barrier
	s_add_i32 s62, s53, s42
	s_add_u32 s80, s30, 0x80
	s_addc_u32 s81, s31, 0
	s_mov_b32 m0, s62
	ds_read_b128 v[200:203], v153
	ds_read_b128 v[204:207], v153 offset:1024
	ds_read_b128 v[208:211], v153 offset:2048
	ds_read_b128 v[212:215], v153 offset:3072
	global_load_lds_dwordx4 v132, s[30:31]
	s_add_i32 m0, s62, 0x2000
	s_nop 0
	global_load_lds_dwordx4 v128, s[30:31]
	s_barrier
	s_waitcnt lgkmcnt(0)
	s_setprio 1
	s_waitcnt lgkmcnt(0)
	v_mfma_f32_16x16x32_bf16 v[116:119], v[200:203], v[168:171], 0
	v_mfma_f32_16x16x32_bf16 v[112:115], v[208:211], v[168:171], 0
	v_mfma_f32_16x16x32_bf16 v[100:103], v[200:203], v[176:179], 0
	v_mfma_f32_16x16x32_bf16 v[96:99], v[208:211], v[176:179], 0
	v_mfma_f32_16x16x32_bf16 v[84:87], v[200:203], v[184:187], 0
	v_mfma_f32_16x16x32_bf16 v[80:83], v[208:211], v[184:187], 0
	v_mfma_f32_16x16x32_bf16 v[68:71], v[200:203], v[192:195], 0
	v_mfma_f32_16x16x32_bf16 v[64:67], v[208:211], v[192:195], 0
	v_mfma_f32_16x16x32_bf16 v[116:119], v[204:207], v[172:175], v[116:119]
	v_mfma_f32_16x16x32_bf16 v[112:115], v[212:215], v[172:175], v[112:115]
	v_mfma_f32_16x16x32_bf16 v[100:103], v[204:207], v[180:183], v[100:103]
	v_mfma_f32_16x16x32_bf16 v[96:99], v[212:215], v[180:183], v[96:99]
	v_mfma_f32_16x16x32_bf16 v[84:87], v[204:207], v[188:191], v[84:87]
	v_mfma_f32_16x16x32_bf16 v[80:83], v[212:215], v[188:191], v[80:83]
	v_mfma_f32_16x16x32_bf16 v[68:71], v[204:207], v[196:199], v[68:71]
	v_mfma_f32_16x16x32_bf16 v[64:67], v[212:215], v[196:199], v[64:67]
	s_setprio 0
	s_mov_b32 m0, s45
	s_add_u32 s82, s34, 0x80
	s_addc_u32 s83, s35, 0
	s_barrier
	ds_read_b128 v[168:171], v152 offset:16384
	ds_read_b128 v[172:175], v152 offset:17408
	ds_read_b128 v[176:179], v152 offset:18432
	ds_read_b128 v[180:183], v152 offset:19456
	ds_read_b128 v[184:187], v152 offset:20480
	ds_read_b128 v[188:191], v152 offset:21504
	ds_read_b128 v[192:195], v152 offset:22528
	ds_read_b128 v[196:199], v152 offset:23552
	global_load_lds_dwordx4 v134, s[34:35]
	s_mov_b32 m0, s46
	s_nop 0
	global_load_lds_dwordx4 v130, s[34:35]
	s_barrier
	s_waitcnt lgkmcnt(0)
	s_setprio 1
	s_waitcnt lgkmcnt(0)
	v_mfma_f32_16x16x32_bf16 v[60:63], v[144:147], v[168:171], 0
	v_mfma_f32_16x16x32_bf16 v[56:59], v[160:163], v[168:171], 0
	v_mfma_f32_16x16x32_bf16 v[44:47], v[144:147], v[176:179], 0
	v_mfma_f32_16x16x32_bf16 v[40:43], v[160:163], v[176:179], 0
	v_mfma_f32_16x16x32_bf16 v[28:31], v[144:147], v[184:187], 0
	v_mfma_f32_16x16x32_bf16 v[24:27], v[160:163], v[184:187], 0
	v_mfma_f32_16x16x32_bf16 v[12:15], v[144:147], v[192:195], 0
	v_mfma_f32_16x16x32_bf16 v[8:11], v[160:163], v[192:195], 0
	v_mfma_f32_16x16x32_bf16 v[60:63], v[156:159], v[172:175], v[60:63]
	v_mfma_f32_16x16x32_bf16 v[56:59], v[164:167], v[172:175], v[56:59]
	v_mfma_f32_16x16x32_bf16 v[44:47], v[156:159], v[180:183], v[44:47]
	v_mfma_f32_16x16x32_bf16 v[40:43], v[164:167], v[180:183], v[40:43]
	v_mfma_f32_16x16x32_bf16 v[28:31], v[156:159], v[188:191], v[28:31]
	v_mfma_f32_16x16x32_bf16 v[24:27], v[164:167], v[188:191], v[24:27]
	v_mfma_f32_16x16x32_bf16 v[12:15], v[156:159], v[196:199], v[12:15]
	v_mfma_f32_16x16x32_bf16 v[8:11], v[164:167], v[196:199], v[8:11]
	s_setprio 0
	s_barrier
	s_add_u32 s62, s30, 0x40000
	s_addc_u32 s63, s31, 0
	s_add_i32 s64, s54, s42
	s_mov_b32 m0, s64
	s_nop 0
	global_load_lds_dwordx4 v132, s[62:63]
	s_add_i32 m0, s64, 0x2000
	s_nop 0
	global_load_lds_dwordx4 v128, s[62:63]
	s_waitcnt vmcnt(6)
	s_barrier
	s_setprio 1
	v_mfma_f32_16x16x32_bf16 v[52:55], v[200:203], v[168:171], 0
	v_mfma_f32_16x16x32_bf16 v[48:51], v[208:211], v[168:171], 0
	v_mfma_f32_16x16x32_bf16 v[36:39], v[200:203], v[176:179], 0
	v_mfma_f32_16x16x32_bf16 v[32:35], v[208:211], v[176:179], 0
	v_mfma_f32_16x16x32_bf16 v[20:23], v[200:203], v[184:187], 0
	v_mfma_f32_16x16x32_bf16 v[16:19], v[208:211], v[184:187], 0
	v_mfma_f32_16x16x32_bf16 v[4:7], v[200:203], v[192:195], 0
	v_mfma_f32_16x16x32_bf16 v[0:3], v[208:211], v[192:195], 0
	v_mfma_f32_16x16x32_bf16 v[52:55], v[204:207], v[172:175], v[52:55]
	v_mfma_f32_16x16x32_bf16 v[48:51], v[212:215], v[172:175], v[48:51]
	v_mfma_f32_16x16x32_bf16 v[36:39], v[204:207], v[180:183], v[36:39]
	v_mfma_f32_16x16x32_bf16 v[32:35], v[212:215], v[180:183], v[32:35]
	v_mfma_f32_16x16x32_bf16 v[20:23], v[204:207], v[188:191], v[20:23]
	v_mfma_f32_16x16x32_bf16 v[16:19], v[212:215], v[188:191], v[16:19]
	v_mfma_f32_16x16x32_bf16 v[4:7], v[204:207], v[196:199], v[4:7]
	v_mfma_f32_16x16x32_bf16 v[0:3], v[212:215], v[196:199], v[0:3]
	s_setprio 0
	s_add_i32 s62, 0, 0x18000
	v_add_u32_e32 v155, s62, v149
	s_barrier
	s_branch .Lg786_mid

.Lg786_mid:
	ds_read_b128 v[144:147], v155
	ds_read_b128 v[156:159], v155 offset:1024
	ds_read_b128 v[160:163], v155 offset:2048
	ds_read_b128 v[164:167], v155 offset:3072
	s_add_u32 s34, s34, 0x40000
	s_addc_u32 s35, s35, 0
	s_mov_b32 m0, s47
	ds_read_b128 v[168:171], v152 offset:32768
	ds_read_b128 v[172:175], v152 offset:33792
	ds_read_b128 v[176:179], v152 offset:34816
	ds_read_b128 v[180:183], v152 offset:35840
	ds_read_b128 v[184:187], v152 offset:36864
	ds_read_b128 v[188:191], v152 offset:37888
	ds_read_b128 v[192:195], v152 offset:38912
	ds_read_b128 v[196:199], v152 offset:39936
	global_load_lds_dwordx4 v134, s[34:35]
	s_mov_b32 m0, s48
	s_nop 0
	global_load_lds_dwordx4 v130, s[34:35]
	s_waitcnt lgkmcnt(8)
	s_barrier
	s_waitcnt lgkmcnt(0)
	s_setprio 1
	s_waitcnt lgkmcnt(0)
	v_mfma_f32_16x16x32_bf16 v[124:127], v[144:147], v[168:171], v[124:127]
	v_mfma_f32_16x16x32_bf16 v[120:123], v[160:163], v[168:171], v[120:123]
	v_mfma_f32_16x16x32_bf16 v[108:111], v[144:147], v[176:179], v[108:111]
	v_mfma_f32_16x16x32_bf16 v[104:107], v[160:163], v[176:179], v[104:107]
	v_mfma_f32_16x16x32_bf16 v[92:95], v[144:147], v[184:187], v[92:95]
	v_mfma_f32_16x16x32_bf16 v[88:91], v[160:163], v[184:187], v[88:91]
	v_mfma_f32_16x16x32_bf16 v[76:79], v[144:147], v[192:195], v[76:79]
	v_mfma_f32_16x16x32_bf16 v[72:75], v[160:163], v[192:195], v[72:75]
	v_mfma_f32_16x16x32_bf16 v[124:127], v[156:159], v[172:175], v[124:127]
	v_mfma_f32_16x16x32_bf16 v[120:123], v[164:167], v[172:175], v[120:123]
	v_mfma_f32_16x16x32_bf16 v[108:111], v[156:159], v[180:183], v[108:111]
	v_mfma_f32_16x16x32_bf16 v[104:107], v[164:167], v[180:183], v[104:107]
	v_mfma_f32_16x16x32_bf16 v[92:95], v[156:159], v[188:191], v[92:95]
	v_mfma_f32_16x16x32_bf16 v[88:91], v[164:167], v[188:191], v[88:91]
	v_mfma_f32_16x16x32_bf16 v[76:79], v[156:159], v[196:199], v[76:79]
	v_mfma_f32_16x16x32_bf16 v[72:75], v[164:167], v[196:199], v[72:75]
	s_setprio 0
	s_barrier
	s_add_i32 s34, 0, 0x1c000
	s_add_i32 s35, s62, s42
	v_add_u32_e32 v155, s34, v149
	s_mov_b32 m0, s35
	ds_read_b128 v[200:203], v155
	ds_read_b128 v[204:207], v155 offset:1024
	ds_read_b128 v[208:211], v155 offset:2048
	ds_read_b128 v[212:215], v155 offset:3072
	global_load_lds_dwordx4 v132, s[80:81]
	s_add_i32 m0, s35, 0x2000
	s_nop 0
	global_load_lds_dwordx4 v128, s[80:81]
	s_barrier
	s_waitcnt lgkmcnt(0)
	s_setprio 1
	s_waitcnt lgkmcnt(0)
	v_mfma_f32_16x16x32_bf16 v[116:119], v[200:203], v[168:171], v[116:119]
	v_mfma_f32_16x16x32_bf16 v[112:115], v[208:211], v[168:171], v[112:115]
	v_mfma_f32_16x16x32_bf16 v[100:103], v[200:203], v[176:179], v[100:103]
	v_mfma_f32_16x16x32_bf16 v[96:99], v[208:211], v[176:179], v[96:99]
	v_mfma_f32_16x16x32_bf16 v[84:87], v[200:203], v[184:187], v[84:87]
	v_mfma_f32_16x16x32_bf16 v[80:83], v[208:211], v[184:187], v[80:83]
	v_mfma_f32_16x16x32_bf16 v[68:71], v[200:203], v[192:195], v[68:71]
	v_mfma_f32_16x16x32_bf16 v[64:67], v[208:211], v[192:195], v[64:67]
	v_mfma_f32_16x16x32_bf16 v[116:119], v[204:207], v[172:175], v[116:119]
	v_mfma_f32_16x16x32_bf16 v[112:115], v[212:215], v[172:175], v[112:115]
	v_mfma_f32_16x16x32_bf16 v[100:103], v[204:207], v[180:183], v[100:103]
	v_mfma_f32_16x16x32_bf16 v[96:99], v[212:215], v[180:183], v[96:99]
	v_mfma_f32_16x16x32_bf16 v[84:87], v[204:207], v[188:191], v[84:87]
	v_mfma_f32_16x16x32_bf16 v[80:83], v[212:215], v[188:191], v[80:83]
	v_mfma_f32_16x16x32_bf16 v[68:71], v[204:207], v[196:199], v[68:71]
	v_mfma_f32_16x16x32_bf16 v[64:67], v[212:215], v[196:199], v[64:67]
	s_setprio 0
	s_mov_b32 m0, s50
	s_barrier
	ds_read_b128 v[168:171], v152 offset:49152
	ds_read_b128 v[172:175], v152 offset:50176
	ds_read_b128 v[176:179], v152 offset:51200
	ds_read_b128 v[180:183], v152 offset:52224
	ds_read_b128 v[184:187], v152 offset:53248
	ds_read_b128 v[188:191], v152 offset:54272
	ds_read_b128 v[192:195], v152 offset:55296
	ds_read_b128 v[196:199], v152 offset:56320
	global_load_lds_dwordx4 v134, s[82:83]
	s_mov_b32 m0, s51
	s_nop 0
	global_load_lds_dwordx4 v130, s[82:83]
	s_barrier
	s_waitcnt lgkmcnt(0)
	s_setprio 1
	s_waitcnt lgkmcnt(0)
	v_mfma_f32_16x16x32_bf16 v[60:63], v[144:147], v[168:171], v[60:63]
	v_mfma_f32_16x16x32_bf16 v[56:59], v[160:163], v[168:171], v[56:59]
	v_mfma_f32_16x16x32_bf16 v[44:47], v[144:147], v[176:179], v[44:47]
	v_mfma_f32_16x16x32_bf16 v[40:43], v[160:163], v[176:179], v[40:43]
	v_mfma_f32_16x16x32_bf16 v[28:31], v[144:147], v[184:187], v[28:31]
	v_mfma_f32_16x16x32_bf16 v[24:27], v[160:163], v[184:187], v[24:27]
	v_mfma_f32_16x16x32_bf16 v[12:15], v[144:147], v[192:195], v[12:15]
	v_mfma_f32_16x16x32_bf16 v[8:11], v[160:163], v[192:195], v[8:11]
	v_mfma_f32_16x16x32_bf16 v[60:63], v[156:159], v[172:175], v[60:63]
	v_mfma_f32_16x16x32_bf16 v[56:59], v[164:167], v[172:175], v[56:59]
	v_mfma_f32_16x16x32_bf16 v[44:47], v[156:159], v[180:183], v[44:47]
	v_mfma_f32_16x16x32_bf16 v[40:43], v[164:167], v[180:183], v[40:43]
	v_mfma_f32_16x16x32_bf16 v[28:31], v[156:159], v[188:191], v[28:31]
	v_mfma_f32_16x16x32_bf16 v[24:27], v[164:167], v[188:191], v[24:27]
	v_mfma_f32_16x16x32_bf16 v[12:15], v[156:159], v[196:199], v[12:15]
	v_mfma_f32_16x16x32_bf16 v[8:11], v[164:167], v[196:199], v[8:11]
	s_setprio 0
	s_barrier
	s_add_u32 s30, s30, 0x40080
	s_addc_u32 s31, s31, 0
	s_add_i32 s34, s34, s42
	s_mov_b32 m0, s34
	s_nop 0
	global_load_lds_dwordx4 v132, s[30:31]
	s_add_i32 m0, s34, 0x2000
	s_nop 0
	global_load_lds_dwordx4 v128, s[30:31]
	s_waitcnt vmcnt(6)
	s_barrier
	s_setprio 1
	v_mfma_f32_16x16x32_bf16 v[52:55], v[200:203], v[168:171], v[52:55]
	v_mfma_f32_16x16x32_bf16 v[48:51], v[208:211], v[168:171], v[48:51]
	v_mfma_f32_16x16x32_bf16 v[36:39], v[200:203], v[176:179], v[36:39]
	v_mfma_f32_16x16x32_bf16 v[32:35], v[208:211], v[176:179], v[32:35]
	v_mfma_f32_16x16x32_bf16 v[20:23], v[200:203], v[184:187], v[20:23]
	v_mfma_f32_16x16x32_bf16 v[16:19], v[208:211], v[184:187], v[16:19]
	v_mfma_f32_16x16x32_bf16 v[4:7], v[200:203], v[192:195], v[4:7]
	v_mfma_f32_16x16x32_bf16 v[0:3], v[208:211], v[192:195], v[0:3]
	v_mfma_f32_16x16x32_bf16 v[52:55], v[204:207], v[172:175], v[52:55]
	v_mfma_f32_16x16x32_bf16 v[48:51], v[212:215], v[172:175], v[48:51]
	v_mfma_f32_16x16x32_bf16 v[36:39], v[204:207], v[180:183], v[36:39]
	v_mfma_f32_16x16x32_bf16 v[32:35], v[212:215], v[180:183], v[32:35]
	v_mfma_f32_16x16x32_bf16 v[20:23], v[204:207], v[188:191], v[20:23]
	v_mfma_f32_16x16x32_bf16 v[16:19], v[212:215], v[188:191], v[16:19]
	v_mfma_f32_16x16x32_bf16 v[4:7], v[204:207], v[196:199], v[4:7]
	v_mfma_f32_16x16x32_bf16 v[0:3], v[212:215], v[196:199], v[0:3]
	s_setprio 0
	s_add_i32 s61, s61, 2
	s_add_u32 s28, s28, 0x100
	s_addc_u32 s29, s29, 0
	s_add_u32 s59, s59, 0x100
	s_addc_u32 s60, s60, 0
	s_cmp_gt_u32 s61, 13
	s_barrier
	s_cbranch_scc0 .LBB0_786
	v_lshl_add_u32 v146, s8, 8, v148
	v_ashrrev_i32_e32 v147, 31, v146
	v_lshl_or_b32 v144, s56, 8, v150
	v_lshlrev_b64 v[156:157], 11, v[146:147]
	v_ashrrev_i32_e32 v145, 31, v144
	v_lshl_add_u64 v[156:157], s[10:11], 0, v[156:157]
	v_lshl_add_u64 v[166:167], v[144:145], 1, v[156:157]
	global_load_dwordx4 v[158:161], v[166:167], off
	global_load_dwordx4 v[162:165], v[166:167], off offset:256
	s_mov_b64 s[84:85], 0x8000
	s_mov_b64 s[86:87], 0x28000
	v_lshl_add_u64 v[232:233], v[166:167], 0, s[84:85]
	global_load_dwordx4 v[176:179], v[232:233], off
	global_load_dwordx4 v[180:183], v[232:233], off offset:256
	v_lshl_add_u64 v[232:233], v[232:233], 0, s[84:85]
	global_load_dwordx4 v[184:187], v[232:233], off
	global_load_dwordx4 v[188:191], v[232:233], off offset:256
	v_lshl_add_u64 v[232:233], v[232:233], 0, s[84:85]
	global_load_dwordx4 v[192:195], v[232:233], off
	global_load_dwordx4 v[196:199], v[232:233], off offset:256
	v_lshl_add_u64 v[232:233], v[232:233], 0, s[86:87]
	global_load_dwordx4 v[200:203], v[232:233], off
	global_load_dwordx4 v[204:207], v[232:233], off offset:256
	v_lshl_add_u64 v[232:233], v[232:233], 0, s[84:85]
	global_load_dwordx4 v[208:211], v[232:233], off
	global_load_dwordx4 v[212:215], v[232:233], off offset:256
	v_lshl_add_u64 v[232:233], v[232:233], 0, s[84:85]
	global_load_dwordx4 v[216:219], v[232:233], off
	global_load_dwordx4 v[220:223], v[232:233], off offset:256
	v_lshl_add_u64 v[232:233], v[232:233], 0, s[84:85]
	global_load_dwordx4 v[224:227], v[232:233], off
	global_load_dwordx4 v[228:231], v[232:233], off offset:256
	s_cmpk_gt_u32 s37, 0xff
	s_cbranch_scc1 .Lg786_nox
	s_barrier

.LBB0_892:
	s_ashr_i32 s13, s12, 31
	v_cmp_lt_i64_e32 vcc, s[14:15], v[140:141]
	s_lshl_b64 s[14:15], s[12:13], 19
	s_add_u32 s14, s37, s14
	s_addc_u32 s15, s38, s15
	s_and_b64 s[16:17], vcc, exec
	s_cselect_b32 s13, s15, s21
	s_cselect_b32 s53, s14, s20
	s_ashr_i32 s11, s10, 31
	s_lshl_b64 s[16:17], s[10:11], 19
	s_add_u32 s16, s39, s16
	s_addc_u32 s17, s40, s17
	s_and_b64 s[28:29], vcc, exec
	s_cselect_b32 s11, s17, s27
	s_cselect_b32 s54, s16, s26
	s_add_u32 s20, s20, 0x40080
	s_addc_u32 s21, s21, 0
	s_add_u32 s55, s26, 0x100
	s_addc_u32 s56, s27, 0
	s_mov_b32 s57, -2
	s_cmpk_lt_u32 s30, 0x100
	s_cbranch_scc1 .Lg893_noy
	s_barrier
.Lg893_noy:
	ds_read_b128 v[152:155], v148
	ds_read_b128 v[156:159], v148 offset:1024
	ds_read_b128 v[160:163], v148 offset:2048
	ds_read_b128 v[164:167], v148 offset:3072
	s_add_u32 s26, s20, 0xfffc0080
	s_addc_u32 s27, s21, -1
	s_cmp_eq_u32 s57, 12
	s_cselect_b32 s29, s13, s27
	s_cselect_b32 s28, s53, s26
	s_cselect_b32 s27, s11, s56
	s_cselect_b32 s26, s54, s55
	s_add_i32 m0, s19, 0xc000
	ds_read_b128 v[168:171], v149
	ds_read_b128 v[172:175], v149 offset:1024
	ds_read_b128 v[176:179], v149 offset:2048
	ds_read_b128 v[180:183], v149 offset:3072
	ds_read_b128 v[184:187], v149 offset:4096
	ds_read_b128 v[188:191], v149 offset:5120
	ds_read_b128 v[192:195], v149 offset:6144
	ds_read_b128 v[196:199], v149 offset:7168
	global_load_lds_dwordx4 v136, s[20:21]
	s_add_i32 m0, s19, 0xe000
	s_nop 0
	global_load_lds_dwordx4 v138, s[20:21]
	s_waitcnt lgkmcnt(8)
	s_barrier
	s_waitcnt lgkmcnt(0)
	s_setprio 1
	s_waitcnt lgkmcnt(0)
	v_mfma_f32_16x16x32_bf16 v[124:127], v[152:155], v[168:171], 0
	v_mfma_f32_16x16x32_bf16 v[120:123], v[160:163], v[168:171], 0
	v_mfma_f32_16x16x32_bf16 v[108:111], v[152:155], v[176:179], 0
	v_mfma_f32_16x16x32_bf16 v[104:107], v[160:163], v[176:179], 0
	v_mfma_f32_16x16x32_bf16 v[92:95], v[152:155], v[184:187], 0
	v_mfma_f32_16x16x32_bf16 v[88:91], v[160:163], v[184:187], 0
	v_mfma_f32_16x16x32_bf16 v[76:79], v[152:155], v[192:195], 0
	v_mfma_f32_16x16x32_bf16 v[72:75], v[160:163], v[192:195], 0
	v_mfma_f32_16x16x32_bf16 v[124:127], v[156:159], v[172:175], v[124:127]
	v_mfma_f32_16x16x32_bf16 v[120:123], v[164:167], v[172:175], v[120:123]
	v_mfma_f32_16x16x32_bf16 v[108:111], v[156:159], v[180:183], v[108:111]
	v_mfma_f32_16x16x32_bf16 v[104:107], v[164:167], v[180:183], v[104:107]
	v_mfma_f32_16x16x32_bf16 v[92:95], v[156:159], v[188:191], v[92:95]
	v_mfma_f32_16x16x32_bf16 v[88:91], v[164:167], v[188:191], v[88:91]
	v_mfma_f32_16x16x32_bf16 v[76:79], v[156:159], v[196:199], v[76:79]
	v_mfma_f32_16x16x32_bf16 v[72:75], v[164:167], v[196:199], v[72:75]
	s_setprio 0
	s_barrier
	s_add_i32 s58, s47, s31
	s_add_u32 s80, s26, 0x80
	s_addc_u32 s81, s27, 0
	s_mov_b32 m0, s58
	ds_read_b128 v[200:203], v150
	ds_read_b128 v[204:207], v150 offset:1024
	ds_read_b128 v[208:211], v150 offset:2048
	ds_read_b128 v[212:215], v150 offset:3072
	global_load_lds_dwordx4 v132, s[26:27]
	s_add_i32 m0, s58, 0x2000
	s_nop 0
	global_load_lds_dwordx4 v128, s[26:27]
	s_barrier
	s_waitcnt lgkmcnt(0)
	s_setprio 1
	s_waitcnt lgkmcnt(0)
	v_mfma_f32_16x16x32_bf16 v[116:119], v[200:203], v[168:171], 0
	v_mfma_f32_16x16x32_bf16 v[112:115], v[208:211], v[168:171], 0
	v_mfma_f32_16x16x32_bf16 v[100:103], v[200:203], v[176:179], 0
	v_mfma_f32_16x16x32_bf16 v[96:99], v[208:211], v[176:179], 0
	v_mfma_f32_16x16x32_bf16 v[84:87], v[200:203], v[184:187], 0
	v_mfma_f32_16x16x32_bf16 v[80:83], v[208:211], v[184:187], 0
	v_mfma_f32_16x16x32_bf16 v[68:71], v[200:203], v[192:195], 0
	v_mfma_f32_16x16x32_bf16 v[64:67], v[208:211], v[192:195], 0
	v_mfma_f32_16x16x32_bf16 v[116:119], v[204:207], v[172:175], v[116:119]
	v_mfma_f32_16x16x32_bf16 v[112:115], v[212:215], v[172:175], v[112:115]
	v_mfma_f32_16x16x32_bf16 v[100:103], v[204:207], v[180:183], v[100:103]
	v_mfma_f32_16x16x32_bf16 v[96:99], v[212:215], v[180:183], v[96:99]
	v_mfma_f32_16x16x32_bf16 v[84:87], v[204:207], v[188:191], v[84:87]
	v_mfma_f32_16x16x32_bf16 v[80:83], v[212:215], v[188:191], v[80:83]
	v_mfma_f32_16x16x32_bf16 v[68:71], v[204:207], v[196:199], v[68:71]
	v_mfma_f32_16x16x32_bf16 v[64:67], v[212:215], v[196:199], v[64:67]
	s_setprio 0
	s_mov_b32 m0, s19
	s_add_u32 s82, s28, 0x80
	s_addc_u32 s83, s29, 0
	s_barrier
	ds_read_b128 v[168:171], v149 offset:16384
	ds_read_b128 v[172:175], v149 offset:17408
	ds_read_b128 v[176:179], v149 offset:18432
	ds_read_b128 v[180:183], v149 offset:19456
	ds_read_b128 v[184:187], v149 offset:20480
	ds_read_b128 v[188:191], v149 offset:21504
	ds_read_b128 v[192:195], v149 offset:22528
	ds_read_b128 v[196:199], v149 offset:23552
	global_load_lds_dwordx4 v134, s[28:29]
	s_mov_b32 m0, s42
	s_nop 0
	global_load_lds_dwordx4 v130, s[28:29]
	s_barrier
	s_waitcnt lgkmcnt(0)
	s_setprio 1
	s_waitcnt lgkmcnt(0)
	v_mfma_f32_16x16x32_bf16 v[60:63], v[152:155], v[168:171], 0
	v_mfma_f32_16x16x32_bf16 v[56:59], v[160:163], v[168:171], 0
	v_mfma_f32_16x16x32_bf16 v[44:47], v[152:155], v[176:179], 0
	v_mfma_f32_16x16x32_bf16 v[40:43], v[160:163], v[176:179], 0
	v_mfma_f32_16x16x32_bf16 v[28:31], v[152:155], v[184:187], 0
	v_mfma_f32_16x16x32_bf16 v[24:27], v[160:163], v[184:187], 0
	v_mfma_f32_16x16x32_bf16 v[12:15], v[152:155], v[192:195], 0
	v_mfma_f32_16x16x32_bf16 v[8:11], v[160:163], v[192:195], 0
	v_mfma_f32_16x16x32_bf16 v[60:63], v[156:159], v[172:175], v[60:63]
	v_mfma_f32_16x16x32_bf16 v[56:59], v[164:167], v[172:175], v[56:59]
	v_mfma_f32_16x16x32_bf16 v[44:47], v[156:159], v[180:183], v[44:47]
	v_mfma_f32_16x16x32_bf16 v[40:43], v[164:167], v[180:183], v[40:43]
	v_mfma_f32_16x16x32_bf16 v[28:31], v[156:159], v[188:191], v[28:31]
	v_mfma_f32_16x16x32_bf16 v[24:27], v[164:167], v[188:191], v[24:27]
	v_mfma_f32_16x16x32_bf16 v[12:15], v[156:159], v[196:199], v[12:15]
	v_mfma_f32_16x16x32_bf16 v[8:11], v[164:167], v[196:199], v[8:11]
	s_setprio 0
	s_barrier
	s_add_u32 s58, s26, 0x40000
	s_addc_u32 s59, s27, 0
	s_add_i32 s60, s48, s31
	s_mov_b32 m0, s60
	s_nop 0
	global_load_lds_dwordx4 v132, s[58:59]
	s_add_i32 m0, s60, 0x2000
	s_nop 0
	global_load_lds_dwordx4 v128, s[58:59]
	s_waitcnt vmcnt(6)
	s_barrier
	s_setprio 1
	v_mfma_f32_16x16x32_bf16 v[52:55], v[200:203], v[168:171], 0
	v_mfma_f32_16x16x32_bf16 v[48:51], v[208:211], v[168:171], 0
	v_mfma_f32_16x16x32_bf16 v[36:39], v[200:203], v[176:179], 0
	v_mfma_f32_16x16x32_bf16 v[32:35], v[208:211], v[176:179], 0
	v_mfma_f32_16x16x32_bf16 v[20:23], v[200:203], v[184:187], 0
	v_mfma_f32_16x16x32_bf16 v[16:19], v[208:211], v[184:187], 0
	v_mfma_f32_16x16x32_bf16 v[4:7], v[200:203], v[192:195], 0
	v_mfma_f32_16x16x32_bf16 v[0:3], v[208:211], v[192:195], 0
	v_mfma_f32_16x16x32_bf16 v[52:55], v[204:207], v[172:175], v[52:55]
	v_mfma_f32_16x16x32_bf16 v[48:51], v[212:215], v[172:175], v[48:51]
	v_mfma_f32_16x16x32_bf16 v[36:39], v[204:207], v[180:183], v[36:39]
	v_mfma_f32_16x16x32_bf16 v[32:35], v[212:215], v[180:183], v[32:35]
	v_mfma_f32_16x16x32_bf16 v[20:23], v[204:207], v[188:191], v[20:23]
	v_mfma_f32_16x16x32_bf16 v[16:19], v[212:215], v[188:191], v[16:19]
	v_mfma_f32_16x16x32_bf16 v[4:7], v[204:207], v[196:199], v[4:7]
	v_mfma_f32_16x16x32_bf16 v[0:3], v[212:215], v[196:199], v[0:3]
	s_setprio 0
	s_add_i32 s58, 0, 0x18000
	v_add_u32_e32 v151, s58, v145
	s_barrier
	s_branch .Lg893_mid

.Lg893_mid:
	ds_read_b128 v[152:155], v151
	ds_read_b128 v[156:159], v151 offset:1024
	ds_read_b128 v[160:163], v151 offset:2048
	ds_read_b128 v[164:167], v151 offset:3072
	s_add_u32 s28, s28, 0x40000
	s_addc_u32 s29, s29, 0
	s_mov_b32 m0, s43
	ds_read_b128 v[168:171], v149 offset:32768
	ds_read_b128 v[172:175], v149 offset:33792
	ds_read_b128 v[176:179], v149 offset:34816
	ds_read_b128 v[180:183], v149 offset:35840
	ds_read_b128 v[184:187], v149 offset:36864
	ds_read_b128 v[188:191], v149 offset:37888
	ds_read_b128 v[192:195], v149 offset:38912
	ds_read_b128 v[196:199], v149 offset:39936
	global_load_lds_dwordx4 v134, s[28:29]
	s_mov_b32 m0, s44
	s_nop 0
	global_load_lds_dwordx4 v130, s[28:29]
	s_waitcnt lgkmcnt(8)
	s_barrier
	s_waitcnt lgkmcnt(0)
	s_setprio 1
	s_waitcnt lgkmcnt(0)
	v_mfma_f32_16x16x32_bf16 v[124:127], v[152:155], v[168:171], v[124:127]
	v_mfma_f32_16x16x32_bf16 v[120:123], v[160:163], v[168:171], v[120:123]
	v_mfma_f32_16x16x32_bf16 v[108:111], v[152:155], v[176:179], v[108:111]
	v_mfma_f32_16x16x32_bf16 v[104:107], v[160:163], v[176:179], v[104:107]
	v_mfma_f32_16x16x32_bf16 v[92:95], v[152:155], v[184:187], v[92:95]
	v_mfma_f32_16x16x32_bf16 v[88:91], v[160:163], v[184:187], v[88:91]
	v_mfma_f32_16x16x32_bf16 v[76:79], v[152:155], v[192:195], v[76:79]
	v_mfma_f32_16x16x32_bf16 v[72:75], v[160:163], v[192:195], v[72:75]
	v_mfma_f32_16x16x32_bf16 v[124:127], v[156:159], v[172:175], v[124:127]
	v_mfma_f32_16x16x32_bf16 v[120:123], v[164:167], v[172:175], v[120:123]
	v_mfma_f32_16x16x32_bf16 v[108:111], v[156:159], v[180:183], v[108:111]
	v_mfma_f32_16x16x32_bf16 v[104:107], v[164:167], v[180:183], v[104:107]
	v_mfma_f32_16x16x32_bf16 v[92:95], v[156:159], v[188:191], v[92:95]
	v_mfma_f32_16x16x32_bf16 v[88:91], v[164:167], v[188:191], v[88:91]
	v_mfma_f32_16x16x32_bf16 v[76:79], v[156:159], v[196:199], v[76:79]
	v_mfma_f32_16x16x32_bf16 v[72:75], v[164:167], v[196:199], v[72:75]
	s_setprio 0
	s_barrier
	s_add_i32 s28, 0, 0x1c000
	s_add_i32 s29, s58, s31
	v_add_u32_e32 v151, s28, v145
	s_mov_b32 m0, s29
	ds_read_b128 v[200:203], v151
	ds_read_b128 v[204:207], v151 offset:1024
	ds_read_b128 v[208:211], v151 offset:2048
	ds_read_b128 v[212:215], v151 offset:3072
	global_load_lds_dwordx4 v132, s[80:81]
	s_add_i32 m0, s29, 0x2000
	s_nop 0
	global_load_lds_dwordx4 v128, s[80:81]
	s_barrier
	s_waitcnt lgkmcnt(0)
	s_setprio 1
	s_waitcnt lgkmcnt(0)
	v_mfma_f32_16x16x32_bf16 v[116:119], v[200:203], v[168:171], v[116:119]
	v_mfma_f32_16x16x32_bf16 v[112:115], v[208:211], v[168:171], v[112:115]
	v_mfma_f32_16x16x32_bf16 v[100:103], v[200:203], v[176:179], v[100:103]
	v_mfma_f32_16x16x32_bf16 v[96:99], v[208:211], v[176:179], v[96:99]
	v_mfma_f32_16x16x32_bf16 v[84:87], v[200:203], v[184:187], v[84:87]
	v_mfma_f32_16x16x32_bf16 v[80:83], v[208:211], v[184:187], v[80:83]
	v_mfma_f32_16x16x32_bf16 v[68:71], v[200:203], v[192:195], v[68:71]
	v_mfma_f32_16x16x32_bf16 v[64:67], v[208:211], v[192:195], v[64:67]
	v_mfma_f32_16x16x32_bf16 v[116:119], v[204:207], v[172:175], v[116:119]
	v_mfma_f32_16x16x32_bf16 v[112:115], v[212:215], v[172:175], v[112:115]
	v_mfma_f32_16x16x32_bf16 v[100:103], v[204:207], v[180:183], v[100:103]
	v_mfma_f32_16x16x32_bf16 v[96:99], v[212:215], v[180:183], v[96:99]
	v_mfma_f32_16x16x32_bf16 v[84:87], v[204:207], v[188:191], v[84:87]
	v_mfma_f32_16x16x32_bf16 v[80:83], v[212:215], v[188:191], v[80:83]
	v_mfma_f32_16x16x32_bf16 v[68:71], v[204:207], v[196:199], v[68:71]
	v_mfma_f32_16x16x32_bf16 v[64:67], v[212:215], v[196:199], v[64:67]
	s_setprio 0
	s_mov_b32 m0, s45
	s_barrier
	ds_read_b128 v[168:171], v149 offset:49152
	ds_read_b128 v[172:175], v149 offset:50176
	ds_read_b128 v[176:179], v149 offset:51200
	ds_read_b128 v[180:183], v149 offset:52224
	ds_read_b128 v[184:187], v149 offset:53248
	ds_read_b128 v[188:191], v149 offset:54272
	ds_read_b128 v[192:195], v149 offset:55296
	ds_read_b128 v[196:199], v149 offset:56320
	global_load_lds_dwordx4 v134, s[82:83]
	s_mov_b32 m0, s46
	s_nop 0
	global_load_lds_dwordx4 v130, s[82:83]
	s_barrier
	s_waitcnt lgkmcnt(0)
	s_setprio 1
	s_waitcnt lgkmcnt(0)
	v_mfma_f32_16x16x32_bf16 v[60:63], v[152:155], v[168:171], v[60:63]
	v_mfma_f32_16x16x32_bf16 v[56:59], v[160:163], v[168:171], v[56:59]
	v_mfma_f32_16x16x32_bf16 v[44:47], v[152:155], v[176:179], v[44:47]
	v_mfma_f32_16x16x32_bf16 v[40:43], v[160:163], v[176:179], v[40:43]
	v_mfma_f32_16x16x32_bf16 v[28:31], v[152:155], v[184:187], v[28:31]
	v_mfma_f32_16x16x32_bf16 v[24:27], v[160:163], v[184:187], v[24:27]
	v_mfma_f32_16x16x32_bf16 v[12:15], v[152:155], v[192:195], v[12:15]
	v_mfma_f32_16x16x32_bf16 v[8:11], v[160:163], v[192:195], v[8:11]
	v_mfma_f32_16x16x32_bf16 v[60:63], v[156:159], v[172:175], v[60:63]
	v_mfma_f32_16x16x32_bf16 v[56:59], v[164:167], v[172:175], v[56:59]
	v_mfma_f32_16x16x32_bf16 v[44:47], v[156:159], v[180:183], v[44:47]
	v_mfma_f32_16x16x32_bf16 v[40:43], v[164:167], v[180:183], v[40:43]
	v_mfma_f32_16x16x32_bf16 v[28:31], v[156:159], v[188:191], v[28:31]
	v_mfma_f32_16x16x32_bf16 v[24:27], v[164:167], v[188:191], v[24:27]
	v_mfma_f32_16x16x32_bf16 v[12:15], v[156:159], v[196:199], v[12:15]
	v_mfma_f32_16x16x32_bf16 v[8:11], v[164:167], v[196:199], v[8:11]
	s_setprio 0
	s_barrier
	s_add_u32 s26, s26, 0x40080
	s_addc_u32 s27, s27, 0
	s_add_i32 s28, s28, s31
	s_mov_b32 m0, s28
	s_nop 0
	global_load_lds_dwordx4 v132, s[26:27]
	s_add_i32 m0, s28, 0x2000
	s_nop 0
	global_load_lds_dwordx4 v128, s[26:27]
	s_waitcnt vmcnt(6)
	s_barrier
	s_setprio 1
	v_mfma_f32_16x16x32_bf16 v[52:55], v[200:203], v[168:171], v[52:55]
	v_mfma_f32_16x16x32_bf16 v[48:51], v[208:211], v[168:171], v[48:51]
	v_mfma_f32_16x16x32_bf16 v[36:39], v[200:203], v[176:179], v[36:39]
	v_mfma_f32_16x16x32_bf16 v[32:35], v[208:211], v[176:179], v[32:35]
	v_mfma_f32_16x16x32_bf16 v[20:23], v[200:203], v[184:187], v[20:23]
	v_mfma_f32_16x16x32_bf16 v[16:19], v[208:211], v[184:187], v[16:19]
	v_mfma_f32_16x16x32_bf16 v[4:7], v[200:203], v[192:195], v[4:7]
	v_mfma_f32_16x16x32_bf16 v[0:3], v[208:211], v[192:195], v[0:3]
	v_mfma_f32_16x16x32_bf16 v[52:55], v[204:207], v[172:175], v[52:55]
	v_mfma_f32_16x16x32_bf16 v[48:51], v[212:215], v[172:175], v[48:51]
	v_mfma_f32_16x16x32_bf16 v[36:39], v[204:207], v[180:183], v[36:39]
	v_mfma_f32_16x16x32_bf16 v[32:35], v[212:215], v[180:183], v[32:35]
	v_mfma_f32_16x16x32_bf16 v[20:23], v[204:207], v[188:191], v[20:23]
	v_mfma_f32_16x16x32_bf16 v[16:19], v[212:215], v[188:191], v[16:19]
	v_mfma_f32_16x16x32_bf16 v[4:7], v[204:207], v[196:199], v[4:7]
	v_mfma_f32_16x16x32_bf16 v[0:3], v[212:215], v[196:199], v[0:3]
	s_setprio 0
	s_add_i32 s57, s57, 2
	s_add_u32 s20, s20, 0x100
	s_addc_u32 s21, s21, 0
	s_add_u32 s55, s55, 0x100
	s_addc_u32 s56, s56, 0
	s_cmp_gt_u32 s57, 13
	s_barrier
	s_cbranch_scc0 .LBB0_893
	s_cmpk_gt_u32 s30, 0xff
	s_cbranch_scc1 .Lg893_nox
	s_barrier

.LBB0_972:
	s_add_u32 s54, s22, 0x100
	s_addc_u32 s55, s23, 0
	s_mov_b32 s56, -2
	s_cmpk_lt_u32 s30, 0x100
	s_cbranch_scc1 .Lg973_noy
	s_barrier
.Lg973_noy:
	ds_read_b128 v[146:149], v203
	ds_read_b128 v[150:153], v203 offset:1024
	ds_read_b128 v[154:157], v203 offset:2048
	ds_read_b128 v[158:161], v203 offset:3072
	s_add_u32 s22, s20, 0x100
	s_addc_u32 s23, s21, 0
	s_cmp_eq_u32 s56, 40
	s_cselect_b32 s27, s5, s23
	s_cselect_b32 s26, s4, s22
	s_cselect_b32 s25, s7, s55
	s_cselect_b32 s24, s6, s54
	s_add_i32 m0, s37, 0xc000
	ds_read_b128 v[162:165], v204
	ds_read_b128 v[166:169], v204 offset:1024
	ds_read_b128 v[170:173], v204 offset:2048
	ds_read_b128 v[174:177], v204 offset:3072
	ds_read_b128 v[178:181], v204 offset:4096
	ds_read_b128 v[182:185], v204 offset:5120
	ds_read_b128 v[186:189], v204 offset:6144
	ds_read_b128 v[190:193], v204 offset:7168
	global_load_lds_dwordx4 v138, s[20:21]
	s_add_i32 m0, s37, 0xe000
	s_nop 0
	global_load_lds_dwordx4 v140, s[20:21]
	s_waitcnt lgkmcnt(8)
	s_barrier
	s_waitcnt lgkmcnt(0)
	s_setprio 1
	s_waitcnt lgkmcnt(0)
	v_mfma_f32_16x16x32_bf16 v[124:127], v[146:149], v[162:165], 0
	v_mfma_f32_16x16x32_bf16 v[120:123], v[154:157], v[162:165], 0
	v_mfma_f32_16x16x32_bf16 v[108:111], v[146:149], v[170:173], 0
	v_mfma_f32_16x16x32_bf16 v[104:107], v[154:157], v[170:173], 0
	v_mfma_f32_16x16x32_bf16 v[92:95], v[146:149], v[178:181], 0
	v_mfma_f32_16x16x32_bf16 v[88:91], v[154:157], v[178:181], 0
	v_mfma_f32_16x16x32_bf16 v[76:79], v[146:149], v[186:189], 0
	v_mfma_f32_16x16x32_bf16 v[72:75], v[154:157], v[186:189], 0
	v_mfma_f32_16x16x32_bf16 v[124:127], v[150:153], v[166:169], v[124:127]
	v_mfma_f32_16x16x32_bf16 v[120:123], v[158:161], v[166:169], v[120:123]
	v_mfma_f32_16x16x32_bf16 v[108:111], v[150:153], v[174:177], v[108:111]
	v_mfma_f32_16x16x32_bf16 v[104:107], v[158:161], v[174:177], v[104:107]
	v_mfma_f32_16x16x32_bf16 v[92:95], v[150:153], v[182:185], v[92:95]
	v_mfma_f32_16x16x32_bf16 v[88:91], v[158:161], v[182:185], v[88:91]
	v_mfma_f32_16x16x32_bf16 v[76:79], v[150:153], v[190:193], v[76:79]
	v_mfma_f32_16x16x32_bf16 v[72:75], v[158:161], v[190:193], v[72:75]
	s_setprio 0
	s_barrier
	s_add_i32 s20, s47, s36
	s_add_u32 s80, s24, 0x80
	s_addc_u32 s81, s25, 0
	s_mov_b32 m0, s20
	ds_read_b128 v[194:197], v205
	ds_read_b128 v[208:211], v205 offset:1024
	ds_read_b128 v[212:215], v205 offset:2048
	ds_read_b128 v[216:219], v205 offset:3072
	global_load_lds_dwordx4 v130, s[24:25]
	s_add_i32 m0, s20, 0x2000
	s_nop 0
	global_load_lds_dwordx4 v134, s[24:25]
	s_barrier
	s_waitcnt lgkmcnt(0)
	s_setprio 1
	s_waitcnt lgkmcnt(0)
	v_mfma_f32_16x16x32_bf16 v[116:119], v[194:197], v[162:165], 0
	v_mfma_f32_16x16x32_bf16 v[112:115], v[212:215], v[162:165], 0
	v_mfma_f32_16x16x32_bf16 v[100:103], v[194:197], v[170:173], 0
	v_mfma_f32_16x16x32_bf16 v[96:99], v[212:215], v[170:173], 0
	v_mfma_f32_16x16x32_bf16 v[84:87], v[194:197], v[178:181], 0
	v_mfma_f32_16x16x32_bf16 v[80:83], v[212:215], v[178:181], 0
	v_mfma_f32_16x16x32_bf16 v[68:71], v[194:197], v[186:189], 0
	v_mfma_f32_16x16x32_bf16 v[64:67], v[212:215], v[186:189], 0
	v_mfma_f32_16x16x32_bf16 v[116:119], v[208:211], v[166:169], v[116:119]
	v_mfma_f32_16x16x32_bf16 v[112:115], v[216:219], v[166:169], v[112:115]
	v_mfma_f32_16x16x32_bf16 v[100:103], v[208:211], v[174:177], v[100:103]
	v_mfma_f32_16x16x32_bf16 v[96:99], v[216:219], v[174:177], v[96:99]
	v_mfma_f32_16x16x32_bf16 v[84:87], v[208:211], v[182:185], v[84:87]
	v_mfma_f32_16x16x32_bf16 v[80:83], v[216:219], v[182:185], v[80:83]
	v_mfma_f32_16x16x32_bf16 v[68:71], v[208:211], v[190:193], v[68:71]
	v_mfma_f32_16x16x32_bf16 v[64:67], v[216:219], v[190:193], v[64:67]
	s_setprio 0
	s_mov_b32 m0, s37
	s_add_u32 s82, s26, 0x80
	s_addc_u32 s83, s27, 0
	s_barrier
	ds_read_b128 v[162:165], v204 offset:16384
	ds_read_b128 v[166:169], v204 offset:17408
	ds_read_b128 v[170:173], v204 offset:18432
	ds_read_b128 v[174:177], v204 offset:19456
	ds_read_b128 v[178:181], v204 offset:20480
	ds_read_b128 v[182:185], v204 offset:21504
	ds_read_b128 v[186:189], v204 offset:22528
	ds_read_b128 v[190:193], v204 offset:23552
	global_load_lds_dwordx4 v128, s[26:27]
	s_mov_b32 m0, s38
	s_nop 0
	global_load_lds_dwordx4 v132, s[26:27]
	s_barrier
	s_waitcnt lgkmcnt(0)
	s_setprio 1
	s_waitcnt lgkmcnt(0)
	v_mfma_f32_16x16x32_bf16 v[60:63], v[146:149], v[162:165], 0
	v_mfma_f32_16x16x32_bf16 v[56:59], v[154:157], v[162:165], 0
	v_mfma_f32_16x16x32_bf16 v[44:47], v[146:149], v[170:173], 0
	v_mfma_f32_16x16x32_bf16 v[40:43], v[154:157], v[170:173], 0
	v_mfma_f32_16x16x32_bf16 v[28:31], v[146:149], v[178:181], 0
	v_mfma_f32_16x16x32_bf16 v[24:27], v[154:157], v[178:181], 0
	v_mfma_f32_16x16x32_bf16 v[12:15], v[146:149], v[186:189], 0
	v_mfma_f32_16x16x32_bf16 v[8:11], v[154:157], v[186:189], 0
	v_mfma_f32_16x16x32_bf16 v[60:63], v[150:153], v[166:169], v[60:63]
	v_mfma_f32_16x16x32_bf16 v[56:59], v[158:161], v[166:169], v[56:59]
	v_mfma_f32_16x16x32_bf16 v[44:47], v[150:153], v[174:177], v[44:47]
	v_mfma_f32_16x16x32_bf16 v[40:43], v[158:161], v[174:177], v[40:43]
	v_mfma_f32_16x16x32_bf16 v[28:31], v[150:153], v[182:185], v[28:31]
	v_mfma_f32_16x16x32_bf16 v[24:27], v[158:161], v[182:185], v[24:27]
	v_mfma_f32_16x16x32_bf16 v[12:15], v[150:153], v[190:193], v[12:15]
	v_mfma_f32_16x16x32_bf16 v[8:11], v[158:161], v[190:193], v[8:11]
	s_setprio 0
	s_barrier
	s_add_u32 s20, s24, 0xb0000
	s_addc_u32 s21, s25, 0
	s_add_i32 s57, s48, s36
	s_mov_b32 m0, s57
	s_nop 0
	global_load_lds_dwordx4 v130, s[20:21]
	s_add_i32 m0, s57, 0x2000
	s_nop 0
	global_load_lds_dwordx4 v134, s[20:21]
	s_waitcnt vmcnt(6)
	s_barrier
	s_setprio 1
	v_mfma_f32_16x16x32_bf16 v[52:55], v[194:197], v[162:165], 0
	v_mfma_f32_16x16x32_bf16 v[48:51], v[212:215], v[162:165], 0
	v_mfma_f32_16x16x32_bf16 v[36:39], v[194:197], v[170:173], 0
	v_mfma_f32_16x16x32_bf16 v[32:35], v[212:215], v[170:173], 0
	v_mfma_f32_16x16x32_bf16 v[20:23], v[194:197], v[178:181], 0
	v_mfma_f32_16x16x32_bf16 v[16:19], v[212:215], v[178:181], 0
	v_mfma_f32_16x16x32_bf16 v[4:7], v[194:197], v[186:189], 0
	v_mfma_f32_16x16x32_bf16 v[0:3], v[212:215], v[186:189], 0
	v_mfma_f32_16x16x32_bf16 v[52:55], v[208:211], v[166:169], v[52:55]
	v_mfma_f32_16x16x32_bf16 v[48:51], v[216:219], v[166:169], v[48:51]
	v_mfma_f32_16x16x32_bf16 v[36:39], v[208:211], v[174:177], v[36:39]
	v_mfma_f32_16x16x32_bf16 v[32:35], v[216:219], v[174:177], v[32:35]
	v_mfma_f32_16x16x32_bf16 v[20:23], v[208:211], v[182:185], v[20:23]
	v_mfma_f32_16x16x32_bf16 v[16:19], v[216:219], v[182:185], v[16:19]
	v_mfma_f32_16x16x32_bf16 v[4:7], v[208:211], v[190:193], v[4:7]
	v_mfma_f32_16x16x32_bf16 v[0:3], v[216:219], v[190:193], v[0:3]
	s_setprio 0
	s_add_i32 s57, 0, 0x18000
	v_add_u32_e32 v158, s57, v201
	s_barrier
	s_branch .Lg973_mid

.Lg973_mid:
	ds_read_b128 v[146:149], v158
	ds_read_b128 v[150:153], v158 offset:1024
	ds_read_b128 v[154:157], v158 offset:2048
	ds_read_b128 v[158:161], v158 offset:3072
	s_add_u32 s20, s26, 0xb0000
	s_addc_u32 s21, s27, 0
	s_mov_b32 m0, s39
	ds_read_b128 v[162:165], v204 offset:32768
	ds_read_b128 v[166:169], v204 offset:33792
	ds_read_b128 v[170:173], v204 offset:34816
	ds_read_b128 v[174:177], v204 offset:35840
	ds_read_b128 v[178:181], v204 offset:36864
	ds_read_b128 v[182:185], v204 offset:37888
	ds_read_b128 v[186:189], v204 offset:38912
	ds_read_b128 v[190:193], v204 offset:39936
	global_load_lds_dwordx4 v128, s[20:21]
	s_mov_b32 m0, s40
	s_nop 0
	global_load_lds_dwordx4 v132, s[20:21]
	s_waitcnt lgkmcnt(8)
	s_barrier
	s_waitcnt lgkmcnt(0)
	s_setprio 1
	s_waitcnt lgkmcnt(0)
	v_mfma_f32_16x16x32_bf16 v[124:127], v[146:149], v[162:165], v[124:127]
	v_mfma_f32_16x16x32_bf16 v[120:123], v[154:157], v[162:165], v[120:123]
	v_mfma_f32_16x16x32_bf16 v[108:111], v[146:149], v[170:173], v[108:111]
	v_mfma_f32_16x16x32_bf16 v[104:107], v[154:157], v[170:173], v[104:107]
	v_mfma_f32_16x16x32_bf16 v[92:95], v[146:149], v[178:181], v[92:95]
	v_mfma_f32_16x16x32_bf16 v[88:91], v[154:157], v[178:181], v[88:91]
	v_mfma_f32_16x16x32_bf16 v[76:79], v[146:149], v[186:189], v[76:79]
	v_mfma_f32_16x16x32_bf16 v[72:75], v[154:157], v[186:189], v[72:75]
	v_mfma_f32_16x16x32_bf16 v[124:127], v[150:153], v[166:169], v[124:127]
	v_mfma_f32_16x16x32_bf16 v[120:123], v[158:161], v[166:169], v[120:123]
	v_mfma_f32_16x16x32_bf16 v[108:111], v[150:153], v[174:177], v[108:111]
	v_mfma_f32_16x16x32_bf16 v[104:107], v[158:161], v[174:177], v[104:107]
	v_mfma_f32_16x16x32_bf16 v[92:95], v[150:153], v[182:185], v[92:95]
	v_mfma_f32_16x16x32_bf16 v[88:91], v[158:161], v[182:185], v[88:91]
	v_mfma_f32_16x16x32_bf16 v[76:79], v[150:153], v[190:193], v[76:79]
	v_mfma_f32_16x16x32_bf16 v[72:75], v[158:161], v[190:193], v[72:75]
	s_setprio 0
	s_barrier
	s_add_i32 s26, 0, 0x1c000
	s_add_i32 s20, s57, s36
	v_add_u32_e32 v216, s26, v201
	s_mov_b32 m0, s20
	ds_read_b128 v[194:197], v216
	ds_read_b128 v[208:211], v216 offset:1024
	ds_read_b128 v[212:215], v216 offset:2048
	ds_read_b128 v[216:219], v216 offset:3072
	global_load_lds_dwordx4 v130, s[80:81]
	s_add_i32 m0, s20, 0x2000
	s_nop 0
	global_load_lds_dwordx4 v134, s[80:81]
	s_barrier
	s_waitcnt lgkmcnt(0)
	s_setprio 1
	s_waitcnt lgkmcnt(0)
	v_mfma_f32_16x16x32_bf16 v[116:119], v[194:197], v[162:165], v[116:119]
	v_mfma_f32_16x16x32_bf16 v[112:115], v[212:215], v[162:165], v[112:115]
	v_mfma_f32_16x16x32_bf16 v[100:103], v[194:197], v[170:173], v[100:103]
	v_mfma_f32_16x16x32_bf16 v[96:99], v[212:215], v[170:173], v[96:99]
	v_mfma_f32_16x16x32_bf16 v[84:87], v[194:197], v[178:181], v[84:87]
	v_mfma_f32_16x16x32_bf16 v[80:83], v[212:215], v[178:181], v[80:83]
	v_mfma_f32_16x16x32_bf16 v[68:71], v[194:197], v[186:189], v[68:71]
	v_mfma_f32_16x16x32_bf16 v[64:67], v[212:215], v[186:189], v[64:67]
	v_mfma_f32_16x16x32_bf16 v[116:119], v[208:211], v[166:169], v[116:119]
	v_mfma_f32_16x16x32_bf16 v[112:115], v[216:219], v[166:169], v[112:115]
	v_mfma_f32_16x16x32_bf16 v[100:103], v[208:211], v[174:177], v[100:103]
	v_mfma_f32_16x16x32_bf16 v[96:99], v[216:219], v[174:177], v[96:99]
	v_mfma_f32_16x16x32_bf16 v[84:87], v[208:211], v[182:185], v[84:87]
	v_mfma_f32_16x16x32_bf16 v[80:83], v[216:219], v[182:185], v[80:83]
	v_mfma_f32_16x16x32_bf16 v[68:71], v[208:211], v[190:193], v[68:71]
	v_mfma_f32_16x16x32_bf16 v[64:67], v[216:219], v[190:193], v[64:67]
	s_setprio 0
	s_mov_b32 m0, s42
	s_barrier
	ds_read_b128 v[162:165], v204 offset:49152
	ds_read_b128 v[166:169], v204 offset:50176
	ds_read_b128 v[170:173], v204 offset:51200
	ds_read_b128 v[174:177], v204 offset:52224
	ds_read_b128 v[178:181], v204 offset:53248
	ds_read_b128 v[182:185], v204 offset:54272
	ds_read_b128 v[186:189], v204 offset:55296
	ds_read_b128 v[190:193], v204 offset:56320
	global_load_lds_dwordx4 v128, s[82:83]
	s_mov_b32 m0, s43
	s_nop 0
	global_load_lds_dwordx4 v132, s[82:83]
	s_barrier
	s_waitcnt lgkmcnt(0)
	s_setprio 1
	s_waitcnt lgkmcnt(0)
	v_mfma_f32_16x16x32_bf16 v[60:63], v[146:149], v[162:165], v[60:63]
	v_mfma_f32_16x16x32_bf16 v[56:59], v[154:157], v[162:165], v[56:59]
	v_mfma_f32_16x16x32_bf16 v[44:47], v[146:149], v[170:173], v[44:47]
	v_mfma_f32_16x16x32_bf16 v[40:43], v[154:157], v[170:173], v[40:43]
	v_mfma_f32_16x16x32_bf16 v[28:31], v[146:149], v[178:181], v[28:31]
	v_mfma_f32_16x16x32_bf16 v[24:27], v[154:157], v[178:181], v[24:27]
	v_mfma_f32_16x16x32_bf16 v[12:15], v[146:149], v[186:189], v[12:15]
	v_mfma_f32_16x16x32_bf16 v[8:11], v[154:157], v[186:189], v[8:11]
	v_mfma_f32_16x16x32_bf16 v[60:63], v[150:153], v[166:169], v[60:63]
	v_mfma_f32_16x16x32_bf16 v[56:59], v[158:161], v[166:169], v[56:59]
	v_mfma_f32_16x16x32_bf16 v[44:47], v[150:153], v[174:177], v[44:47]
	v_mfma_f32_16x16x32_bf16 v[40:43], v[158:161], v[174:177], v[40:43]
	v_mfma_f32_16x16x32_bf16 v[28:31], v[150:153], v[182:185], v[28:31]
	v_mfma_f32_16x16x32_bf16 v[24:27], v[158:161], v[182:185], v[24:27]
	v_mfma_f32_16x16x32_bf16 v[12:15], v[150:153], v[190:193], v[12:15]
	v_mfma_f32_16x16x32_bf16 v[8:11], v[158:161], v[190:193], v[8:11]
	s_setprio 0
	s_barrier
	s_add_u32 s20, s24, 0xb0080
	s_addc_u32 s21, s25, 0
	s_add_i32 s24, s26, s36
	s_mov_b32 m0, s24
	s_nop 0
	global_load_lds_dwordx4 v130, s[20:21]
	s_add_i32 m0, s24, 0x2000
	s_nop 0
	global_load_lds_dwordx4 v134, s[20:21]
	s_waitcnt vmcnt(6)
	s_barrier
	s_setprio 1
	v_mfma_f32_16x16x32_bf16 v[52:55], v[194:197], v[162:165], v[52:55]
	v_mfma_f32_16x16x32_bf16 v[48:51], v[212:215], v[162:165], v[48:51]
	v_mfma_f32_16x16x32_bf16 v[36:39], v[194:197], v[170:173], v[36:39]
	v_mfma_f32_16x16x32_bf16 v[32:35], v[212:215], v[170:173], v[32:35]
	v_mfma_f32_16x16x32_bf16 v[20:23], v[194:197], v[178:181], v[20:23]
	v_mfma_f32_16x16x32_bf16 v[16:19], v[212:215], v[178:181], v[16:19]
	v_mfma_f32_16x16x32_bf16 v[4:7], v[194:197], v[186:189], v[4:7]
	v_mfma_f32_16x16x32_bf16 v[0:3], v[212:215], v[186:189], v[0:3]
	v_mfma_f32_16x16x32_bf16 v[52:55], v[208:211], v[166:169], v[52:55]
	v_mfma_f32_16x16x32_bf16 v[48:51], v[216:219], v[166:169], v[48:51]
	v_mfma_f32_16x16x32_bf16 v[36:39], v[208:211], v[174:177], v[36:39]
	v_mfma_f32_16x16x32_bf16 v[32:35], v[216:219], v[174:177], v[32:35]
	v_mfma_f32_16x16x32_bf16 v[20:23], v[208:211], v[182:185], v[20:23]
	v_mfma_f32_16x16x32_bf16 v[16:19], v[216:219], v[182:185], v[16:19]
	v_mfma_f32_16x16x32_bf16 v[4:7], v[208:211], v[190:193], v[4:7]
	v_mfma_f32_16x16x32_bf16 v[0:3], v[216:219], v[190:193], v[0:3]
	s_setprio 0
	s_add_i32 s56, s56, 2
	s_add_u32 s54, s54, 0x100
	s_addc_u32 s55, s55, 0
	s_cmp_gt_u32 s56, 41
	s_mov_b64 s[20:21], s[22:23]
	s_barrier
	s_cbranch_scc0 .LBB0_973
	s_cmpk_gt_u32 s30, 0xff
	s_cbranch_scc1 .Lg973_nox
	s_barrier
